# DSA prompt path: indexer head loop hand-pipelined (abs-fma, LDS prefetch), PV gather 16 rows in flight
# speedup vs baseline: 1.0361x; 1.0361x over previous
; __device__ __forceinline__ void dsa_unit(int wv, const Args& A, LAS unsigned char* lds, int s, int qt) {
;     ...
;         if (kt < ntiles) {
;             f32x4 sc[4];
; #pragma unroll
;             for (int t = 0; t < 4; ++t) sc[t] = (f32x4){0.f, 0.f, 0.f, 0.f};
; #pragma unroll 2
;             for (int hh = 0; hh < 16; ++hh) {
;                 const h16x8 q0 = __builtin_bit_cast(h16x8, Ql[(hh * 2) * 64 + lane]), q1 = __builtin_bit_cast(h16x8, Ql[(hh * 2 + 1) * 64 + lane]);
;                 const float wh = wql[hh * 16 + fr];
;                 f32x4 a[4];
; #pragma unroll
;                 for (int t = 0; t < 4; ++t) a[t] = __builtin_amdgcn_mfma_f32_16x16x32_f16(kc[t][0], q0, (f32x4){0.f, 0.f, 0.f, 0.f}, 0, 0, 0);
; #pragma unroll
;                 for (int t = 0; t < 4; ++t) a[t] = __builtin_amdgcn_mfma_f32_16x16x32_f16(kc[t][1], q1, a[t], 0, 0, 0);
; #pragma unroll
;                 for (int t = 0; t < 4; ++t)
; #pragma unroll
;                     for (int r = 0; r < 4; ++r) sc[t][r] += wh * fabsf(a[t][r]);
;             }
.LBB0_934:
	s_cmp_ge_i32 s70, s81
	s_cbranch_scc1 .LBB0_1001
	v_mov_b32_e32 v66, 0
	v_mov_b32_e32 v67, 0
	v_mov_b32_e32 v68, 0
	v_mov_b32_e32 v69, 0
	v_mov_b32_e32 v70, 0
	v_mov_b32_e32 v71, 0
	v_mov_b32_e32 v72, 0
	v_mov_b32_e32 v73, 0
	v_mov_b32_e32 v74, 0
	v_mov_b32_e32 v75, 0
	v_mov_b32_e32 v76, 0
	v_mov_b32_e32 v77, 0
	v_mov_b32_e32 v78, 0
	v_mov_b32_e32 v79, 0
	v_mov_b32_e32 v80, 0
	v_mov_b32_e32 v81, 0
	v_add_u32_e32 v145, 0x25480, v109
	ds_read_b128 v[178:181], v112
	ds_read_b128 v[182:185], v112 offset:1024
	ds_read_b32 v186, v145
	ds_read_b128 v[188:191], v112 offset:2048
	ds_read_b128 v[192:195], v112 offset:3072
	ds_read_b32 v196, v145 offset:64
	s_waitcnt lgkmcnt(5)
	v_mfma_f32_16x16x32_f16 v[208:211], v[58:61], v[178:181], 0
	v_mfma_f32_16x16x32_f16 v[212:215], v[62:65], v[178:181], 0
	v_mfma_f32_16x16x32_f16 v[216:219], v[46:49], v[178:181], 0
	v_mfma_f32_16x16x32_f16 v[220:223], v[42:45], v[178:181], 0
	s_waitcnt lgkmcnt(4)
	v_mfma_f32_16x16x32_f16 v[208:211], v[54:57], v[182:185], v[208:211]
	v_mfma_f32_16x16x32_f16 v[212:215], v[50:53], v[182:185], v[212:215]
	v_mfma_f32_16x16x32_f16 v[216:219], v[38:41], v[182:185], v[216:219]
	v_mfma_f32_16x16x32_f16 v[220:223], v[34:37], v[182:185], v[220:223]
	ds_read_b128 v[198:201], v112 offset:4096
	ds_read_b128 v[202:205], v112 offset:5120
	ds_read_b32 v206, v145 offset:128
	s_waitcnt lgkmcnt(3)
	v_mfma_f32_16x16x32_f16 v[224:227], v[58:61], v[188:191], 0
	v_fma_f32 v74, |v208|, v186, v74
	v_fma_f32 v75, |v209|, v186, v75
	v_mfma_f32_16x16x32_f16 v[228:231], v[62:65], v[188:191], 0
	v_fma_f32 v76, |v210|, v186, v76
	v_fma_f32 v77, |v211|, v186, v77
	v_mfma_f32_16x16x32_f16 v[232:235], v[46:49], v[188:191], 0
	v_fma_f32 v78, |v212|, v186, v78
	v_fma_f32 v79, |v213|, v186, v79
	v_mfma_f32_16x16x32_f16 v[240:243], v[42:45], v[188:191], 0
	v_fma_f32 v80, |v214|, v186, v80
	v_fma_f32 v81, |v215|, v186, v81
	v_mfma_f32_16x16x32_f16 v[224:227], v[54:57], v[192:195], v[224:227]
	v_fma_f32 v70, |v216|, v186, v70
	v_fma_f32 v71, |v217|, v186, v71
	v_mfma_f32_16x16x32_f16 v[228:231], v[50:53], v[192:195], v[228:231]
	v_fma_f32 v72, |v218|, v186, v72
	v_fma_f32 v73, |v219|, v186, v73
	v_mfma_f32_16x16x32_f16 v[232:235], v[38:41], v[192:195], v[232:235]
	v_fma_f32 v66, |v220|, v186, v66
	v_fma_f32 v67, |v221|, v186, v67
	v_mfma_f32_16x16x32_f16 v[240:243], v[34:37], v[192:195], v[240:243]
	v_fma_f32 v68, |v222|, v186, v68
	v_fma_f32 v69, |v223|, v186, v69
	ds_read_b128 v[178:181], v112 offset:6144
	ds_read_b128 v[182:185], v112 offset:7168
	ds_read_b32 v186, v145 offset:192
	s_waitcnt lgkmcnt(3)
	v_mfma_f32_16x16x32_f16 v[208:211], v[58:61], v[198:201], 0
	v_fma_f32 v74, |v224|, v196, v74
	v_fma_f32 v75, |v225|, v196, v75
	v_mfma_f32_16x16x32_f16 v[212:215], v[62:65], v[198:201], 0
	v_fma_f32 v76, |v226|, v196, v76
	v_fma_f32 v77, |v227|, v196, v77
	v_mfma_f32_16x16x32_f16 v[216:219], v[46:49], v[198:201], 0
	v_fma_f32 v78, |v228|, v196, v78
	v_fma_f32 v79, |v229|, v196, v79
	v_mfma_f32_16x16x32_f16 v[220:223], v[42:45], v[198:201], 0
	v_fma_f32 v80, |v230|, v196, v80
	v_fma_f32 v81, |v231|, v196, v81
	v_mfma_f32_16x16x32_f16 v[208:211], v[54:57], v[202:205], v[208:211]
	v_fma_f32 v70, |v232|, v196, v70
	v_fma_f32 v71, |v233|, v196, v71
	v_mfma_f32_16x16x32_f16 v[212:215], v[50:53], v[202:205], v[212:215]
	v_fma_f32 v72, |v234|, v196, v72
	v_fma_f32 v73, |v235|, v196, v73
	v_mfma_f32_16x16x32_f16 v[216:219], v[38:41], v[202:205], v[216:219]
	v_fma_f32 v66, |v240|, v196, v66
	v_fma_f32 v67, |v241|, v196, v67
	v_mfma_f32_16x16x32_f16 v[220:223], v[34:37], v[202:205], v[220:223]
	v_fma_f32 v68, |v242|, v196, v68
	v_fma_f32 v69, |v243|, v196, v69
	ds_read_b128 v[188:191], v112 offset:8192
	ds_read_b128 v[192:195], v112 offset:9216
	ds_read_b32 v196, v145 offset:256
	s_waitcnt lgkmcnt(3)
	v_mfma_f32_16x16x32_f16 v[224:227], v[58:61], v[178:181], 0
	v_fma_f32 v74, |v208|, v206, v74
	v_fma_f32 v75, |v209|, v206, v75
	v_mfma_f32_16x16x32_f16 v[228:231], v[62:65], v[178:181], 0
	v_fma_f32 v76, |v210|, v206, v76
	v_fma_f32 v77, |v211|, v206, v77
	v_mfma_f32_16x16x32_f16 v[232:235], v[46:49], v[178:181], 0
	v_fma_f32 v78, |v212|, v206, v78
	v_fma_f32 v79, |v213|, v206, v79
	v_mfma_f32_16x16x32_f16 v[240:243], v[42:45], v[178:181], 0
	v_fma_f32 v80, |v214|, v206, v80
	v_fma_f32 v81, |v215|, v206, v81
	v_mfma_f32_16x16x32_f16 v[224:227], v[54:57], v[182:185], v[224:227]
	v_fma_f32 v70, |v216|, v206, v70
	v_fma_f32 v71, |v217|, v206, v71
	v_mfma_f32_16x16x32_f16 v[228:231], v[50:53], v[182:185], v[228:231]
	v_fma_f32 v72, |v218|, v206, v72
	v_fma_f32 v73, |v219|, v206, v73
	v_mfma_f32_16x16x32_f16 v[232:235], v[38:41], v[182:185], v[232:235]
	v_fma_f32 v66, |v220|, v206, v66
	v_fma_f32 v67, |v221|, v206, v67
	v_mfma_f32_16x16x32_f16 v[240:243], v[34:37], v[182:185], v[240:243]
	v_fma_f32 v68, |v222|, v206, v68
	v_fma_f32 v69, |v223|, v206, v69
	ds_read_b128 v[198:201], v112 offset:10240
	ds_read_b128 v[202:205], v112 offset:11264
	ds_read_b32 v206, v145 offset:320
	s_waitcnt lgkmcnt(3)
	v_mfma_f32_16x16x32_f16 v[208:211], v[58:61], v[188:191], 0
	v_fma_f32 v74, |v224|, v186, v74
	v_fma_f32 v75, |v225|, v186, v75
	v_mfma_f32_16x16x32_f16 v[212:215], v[62:65], v[188:191], 0
	v_fma_f32 v76, |v226|, v186, v76
	v_fma_f32 v77, |v227|, v186, v77
	v_mfma_f32_16x16x32_f16 v[216:219], v[46:49], v[188:191], 0
	v_fma_f32 v78, |v228|, v186, v78
	v_fma_f32 v79, |v229|, v186, v79
	v_mfma_f32_16x16x32_f16 v[220:223], v[42:45], v[188:191], 0
	v_fma_f32 v80, |v230|, v186, v80
	v_fma_f32 v81, |v231|, v186, v81
	v_mfma_f32_16x16x32_f16 v[208:211], v[54:57], v[192:195], v[208:211]
	v_fma_f32 v70, |v232|, v186, v70
	v_fma_f32 v71, |v233|, v186, v71
	v_mfma_f32_16x16x32_f16 v[212:215], v[50:53], v[192:195], v[212:215]
	v_fma_f32 v72, |v234|, v186, v72
	v_fma_f32 v73, |v235|, v186, v73
	v_mfma_f32_16x16x32_f16 v[216:219], v[38:41], v[192:195], v[216:219]
	v_fma_f32 v66, |v240|, v186, v66
	v_fma_f32 v67, |v241|, v186, v67
	v_mfma_f32_16x16x32_f16 v[220:223], v[34:37], v[192:195], v[220:223]
	v_fma_f32 v68, |v242|, v186, v68
	v_fma_f32 v69, |v243|, v186, v69
	ds_read_b128 v[178:181], v112 offset:12288
	ds_read_b128 v[182:185], v112 offset:13312
	ds_read_b32 v186, v145 offset:384
	s_waitcnt lgkmcnt(3)
; __device__ __forceinline__ void dsa_unit(int wv, const Args& A, LAS unsigned char* lds, int s, int qt) {
;     ...
;             for (int hh = 0; hh < 16; ++hh) {
;                 const h16x8 q0 = __builtin_bit_cast(h16x8, Ql[(hh * 2) * 64 + lane]), q1 = __builtin_bit_cast(h16x8, Ql[(hh * 2 + 1) * 64 + lane]);
;                 const float wh = wql[hh * 16 + fr];
;                 f32x4 a[4];
; #pragma unroll
;                 for (int t = 0; t < 4; ++t) a[t] = __builtin_amdgcn_mfma_f32_16x16x32_f16(kc[t][0], q0, (f32x4){0.f, 0.f, 0.f, 0.f}, 0, 0, 0);
; #pragma unroll
;                 for (int t = 0; t < 4; ++t) a[t] = __builtin_amdgcn_mfma_f32_16x16x32_f16(kc[t][1], q1, a[t], 0, 0, 0);
; #pragma unroll
;                 for (int t = 0; t < 4; ++t)
; #pragma unroll
;                     for (int r = 0; r < 4; ++r) sc[t][r] += wh * fabsf(a[t][r]);
;             }
	v_mfma_f32_16x16x32_f16 v[224:227], v[58:61], v[198:201], 0
	v_fma_f32 v74, |v208|, v196, v74
	v_fma_f32 v75, |v209|, v196, v75
	v_mfma_f32_16x16x32_f16 v[228:231], v[62:65], v[198:201], 0
	v_fma_f32 v76, |v210|, v196, v76
	v_fma_f32 v77, |v211|, v196, v77
	v_mfma_f32_16x16x32_f16 v[232:235], v[46:49], v[198:201], 0
	v_fma_f32 v78, |v212|, v196, v78
	v_fma_f32 v79, |v213|, v196, v79
	v_mfma_f32_16x16x32_f16 v[240:243], v[42:45], v[198:201], 0
	v_fma_f32 v80, |v214|, v196, v80
	v_fma_f32 v81, |v215|, v196, v81
	v_mfma_f32_16x16x32_f16 v[224:227], v[54:57], v[202:205], v[224:227]
	v_fma_f32 v70, |v216|, v196, v70
	v_fma_f32 v71, |v217|, v196, v71
	v_mfma_f32_16x16x32_f16 v[228:231], v[50:53], v[202:205], v[228:231]
	v_fma_f32 v72, |v218|, v196, v72
	v_fma_f32 v73, |v219|, v196, v73
	v_mfma_f32_16x16x32_f16 v[232:235], v[38:41], v[202:205], v[232:235]
	v_fma_f32 v66, |v220|, v196, v66
	v_fma_f32 v67, |v221|, v196, v67
	v_mfma_f32_16x16x32_f16 v[240:243], v[34:37], v[202:205], v[240:243]
	v_fma_f32 v68, |v222|, v196, v68
	v_fma_f32 v69, |v223|, v196, v69
	ds_read_b128 v[188:191], v112 offset:14336
	ds_read_b128 v[192:195], v112 offset:15360
	ds_read_b32 v196, v145 offset:448
	s_waitcnt lgkmcnt(3)
	v_mfma_f32_16x16x32_f16 v[208:211], v[58:61], v[178:181], 0
	v_fma_f32 v74, |v224|, v206, v74
	v_fma_f32 v75, |v225|, v206, v75
	v_mfma_f32_16x16x32_f16 v[212:215], v[62:65], v[178:181], 0
	v_fma_f32 v76, |v226|, v206, v76
	v_fma_f32 v77, |v227|, v206, v77
	v_mfma_f32_16x16x32_f16 v[216:219], v[46:49], v[178:181], 0
	v_fma_f32 v78, |v228|, v206, v78
	v_fma_f32 v79, |v229|, v206, v79
	v_mfma_f32_16x16x32_f16 v[220:223], v[42:45], v[178:181], 0
	v_fma_f32 v80, |v230|, v206, v80
	v_fma_f32 v81, |v231|, v206, v81
	v_mfma_f32_16x16x32_f16 v[208:211], v[54:57], v[182:185], v[208:211]
	v_fma_f32 v70, |v232|, v206, v70
	v_fma_f32 v71, |v233|, v206, v71
	v_mfma_f32_16x16x32_f16 v[212:215], v[50:53], v[182:185], v[212:215]
	v_fma_f32 v72, |v234|, v206, v72
	v_fma_f32 v73, |v235|, v206, v73
	v_mfma_f32_16x16x32_f16 v[216:219], v[38:41], v[182:185], v[216:219]
	v_fma_f32 v66, |v240|, v206, v66
	v_fma_f32 v67, |v241|, v206, v67
	v_mfma_f32_16x16x32_f16 v[220:223], v[34:37], v[182:185], v[220:223]
	v_fma_f32 v68, |v242|, v206, v68
	v_fma_f32 v69, |v243|, v206, v69
	ds_read_b128 v[198:201], v112 offset:16384
	ds_read_b128 v[202:205], v112 offset:17408
	ds_read_b32 v206, v145 offset:512
	s_waitcnt lgkmcnt(3)
	v_mfma_f32_16x16x32_f16 v[224:227], v[58:61], v[188:191], 0
	v_fma_f32 v74, |v208|, v186, v74
	v_fma_f32 v75, |v209|, v186, v75
	v_mfma_f32_16x16x32_f16 v[228:231], v[62:65], v[188:191], 0
	v_fma_f32 v76, |v210|, v186, v76
	v_fma_f32 v77, |v211|, v186, v77
	v_mfma_f32_16x16x32_f16 v[232:235], v[46:49], v[188:191], 0
	v_fma_f32 v78, |v212|, v186, v78
	v_fma_f32 v79, |v213|, v186, v79
	v_mfma_f32_16x16x32_f16 v[240:243], v[42:45], v[188:191], 0
	v_fma_f32 v80, |v214|, v186, v80
	v_fma_f32 v81, |v215|, v186, v81
	v_mfma_f32_16x16x32_f16 v[224:227], v[54:57], v[192:195], v[224:227]
	v_fma_f32 v70, |v216|, v186, v70
	v_fma_f32 v71, |v217|, v186, v71
	v_mfma_f32_16x16x32_f16 v[228:231], v[50:53], v[192:195], v[228:231]
	v_fma_f32 v72, |v218|, v186, v72
	v_fma_f32 v73, |v219|, v186, v73
	v_mfma_f32_16x16x32_f16 v[232:235], v[38:41], v[192:195], v[232:235]
	v_fma_f32 v66, |v220|, v186, v66
	v_fma_f32 v67, |v221|, v186, v67
	v_mfma_f32_16x16x32_f16 v[240:243], v[34:37], v[192:195], v[240:243]
	v_fma_f32 v68, |v222|, v186, v68
	v_fma_f32 v69, |v223|, v186, v69
	ds_read_b128 v[178:181], v112 offset:18432
	ds_read_b128 v[182:185], v112 offset:19456
	ds_read_b32 v186, v145 offset:576
	s_waitcnt lgkmcnt(3)
	v_mfma_f32_16x16x32_f16 v[208:211], v[58:61], v[198:201], 0
	v_fma_f32 v74, |v224|, v196, v74
	v_fma_f32 v75, |v225|, v196, v75
	v_mfma_f32_16x16x32_f16 v[212:215], v[62:65], v[198:201], 0
	v_fma_f32 v76, |v226|, v196, v76
	v_fma_f32 v77, |v227|, v196, v77
	v_mfma_f32_16x16x32_f16 v[216:219], v[46:49], v[198:201], 0
	v_fma_f32 v78, |v228|, v196, v78
	v_fma_f32 v79, |v229|, v196, v79
	v_mfma_f32_16x16x32_f16 v[220:223], v[42:45], v[198:201], 0
	v_fma_f32 v80, |v230|, v196, v80
	v_fma_f32 v81, |v231|, v196, v81
	v_mfma_f32_16x16x32_f16 v[208:211], v[54:57], v[202:205], v[208:211]
	v_fma_f32 v70, |v232|, v196, v70
	v_fma_f32 v71, |v233|, v196, v71
	v_mfma_f32_16x16x32_f16 v[212:215], v[50:53], v[202:205], v[212:215]
	v_fma_f32 v72, |v234|, v196, v72
	v_fma_f32 v73, |v235|, v196, v73
	v_mfma_f32_16x16x32_f16 v[216:219], v[38:41], v[202:205], v[216:219]
	v_fma_f32 v66, |v240|, v196, v66
	v_fma_f32 v67, |v241|, v196, v67
	v_mfma_f32_16x16x32_f16 v[220:223], v[34:37], v[202:205], v[220:223]
	v_fma_f32 v68, |v242|, v196, v68
	v_fma_f32 v69, |v243|, v196, v69
	ds_read_b128 v[188:191], v112 offset:20480
	ds_read_b128 v[192:195], v112 offset:21504
	ds_read_b32 v196, v145 offset:640
	s_waitcnt lgkmcnt(3)
	v_mfma_f32_16x16x32_f16 v[224:227], v[58:61], v[178:181], 0
	v_fma_f32 v74, |v208|, v206, v74
	v_fma_f32 v75, |v209|, v206, v75
	v_mfma_f32_16x16x32_f16 v[228:231], v[62:65], v[178:181], 0
	v_fma_f32 v76, |v210|, v206, v76
	v_fma_f32 v77, |v211|, v206, v77
	v_mfma_f32_16x16x32_f16 v[232:235], v[46:49], v[178:181], 0
	v_fma_f32 v78, |v212|, v206, v78
	v_fma_f32 v79, |v213|, v206, v79
	v_mfma_f32_16x16x32_f16 v[240:243], v[42:45], v[178:181], 0
	v_fma_f32 v80, |v214|, v206, v80
	v_fma_f32 v81, |v215|, v206, v81
	v_mfma_f32_16x16x32_f16 v[224:227], v[54:57], v[182:185], v[224:227]
	v_fma_f32 v70, |v216|, v206, v70
	v_fma_f32 v71, |v217|, v206, v71
	v_mfma_f32_16x16x32_f16 v[228:231], v[50:53], v[182:185], v[228:231]
	v_fma_f32 v72, |v218|, v206, v72
	v_fma_f32 v73, |v219|, v206, v73
	v_mfma_f32_16x16x32_f16 v[232:235], v[38:41], v[182:185], v[232:235]
	v_fma_f32 v66, |v220|, v206, v66
	v_fma_f32 v67, |v221|, v206, v67
	v_mfma_f32_16x16x32_f16 v[240:243], v[34:37], v[182:185], v[240:243]
	v_fma_f32 v68, |v222|, v206, v68
	v_fma_f32 v69, |v223|, v206, v69
	ds_read_b128 v[198:201], v112 offset:22528
	ds_read_b128 v[202:205], v112 offset:23552
	ds_read_b32 v206, v145 offset:704
	s_waitcnt lgkmcnt(3)
; __device__ __forceinline__ void dsa_unit(int wv, const Args& A, LAS unsigned char* lds, int s, int qt) {
;     ...
;             for (int hh = 0; hh < 16; ++hh) {
;                 const h16x8 q0 = __builtin_bit_cast(h16x8, Ql[(hh * 2) * 64 + lane]), q1 = __builtin_bit_cast(h16x8, Ql[(hh * 2 + 1) * 64 + lane]);
;                 const float wh = wql[hh * 16 + fr];
;                 f32x4 a[4];
; #pragma unroll
;                 for (int t = 0; t < 4; ++t) a[t] = __builtin_amdgcn_mfma_f32_16x16x32_f16(kc[t][0], q0, (f32x4){0.f, 0.f, 0.f, 0.f}, 0, 0, 0);
; #pragma unroll
;                 for (int t = 0; t < 4; ++t) a[t] = __builtin_amdgcn_mfma_f32_16x16x32_f16(kc[t][1], q1, a[t], 0, 0, 0);
; #pragma unroll
;                 for (int t = 0; t < 4; ++t)
; #pragma unroll
;                     for (int r = 0; r < 4; ++r) sc[t][r] += wh * fabsf(a[t][r]);
;             }
	v_mfma_f32_16x16x32_f16 v[208:211], v[58:61], v[188:191], 0
	v_fma_f32 v74, |v224|, v186, v74
	v_fma_f32 v75, |v225|, v186, v75
	v_mfma_f32_16x16x32_f16 v[212:215], v[62:65], v[188:191], 0
	v_fma_f32 v76, |v226|, v186, v76
	v_fma_f32 v77, |v227|, v186, v77
	v_mfma_f32_16x16x32_f16 v[216:219], v[46:49], v[188:191], 0
	v_fma_f32 v78, |v228|, v186, v78
	v_fma_f32 v79, |v229|, v186, v79
	v_mfma_f32_16x16x32_f16 v[220:223], v[42:45], v[188:191], 0
	v_fma_f32 v80, |v230|, v186, v80
	v_fma_f32 v81, |v231|, v186, v81
	v_mfma_f32_16x16x32_f16 v[208:211], v[54:57], v[192:195], v[208:211]
	v_fma_f32 v70, |v232|, v186, v70
	v_fma_f32 v71, |v233|, v186, v71
	v_mfma_f32_16x16x32_f16 v[212:215], v[50:53], v[192:195], v[212:215]
	v_fma_f32 v72, |v234|, v186, v72
	v_fma_f32 v73, |v235|, v186, v73
	v_mfma_f32_16x16x32_f16 v[216:219], v[38:41], v[192:195], v[216:219]
	v_fma_f32 v66, |v240|, v186, v66
	v_fma_f32 v67, |v241|, v186, v67
	v_mfma_f32_16x16x32_f16 v[220:223], v[34:37], v[192:195], v[220:223]
	v_fma_f32 v68, |v242|, v186, v68
	v_fma_f32 v69, |v243|, v186, v69
	ds_read_b128 v[178:181], v112 offset:24576
	ds_read_b128 v[182:185], v112 offset:25600
	ds_read_b32 v186, v145 offset:768
	s_waitcnt lgkmcnt(3)
	v_mfma_f32_16x16x32_f16 v[224:227], v[58:61], v[198:201], 0
	v_fma_f32 v74, |v208|, v196, v74
	v_fma_f32 v75, |v209|, v196, v75
	v_mfma_f32_16x16x32_f16 v[228:231], v[62:65], v[198:201], 0
	v_fma_f32 v76, |v210|, v196, v76
	v_fma_f32 v77, |v211|, v196, v77
	v_mfma_f32_16x16x32_f16 v[232:235], v[46:49], v[198:201], 0
	v_fma_f32 v78, |v212|, v196, v78
	v_fma_f32 v79, |v213|, v196, v79
	v_mfma_f32_16x16x32_f16 v[240:243], v[42:45], v[198:201], 0
	v_fma_f32 v80, |v214|, v196, v80
	v_fma_f32 v81, |v215|, v196, v81
	v_mfma_f32_16x16x32_f16 v[224:227], v[54:57], v[202:205], v[224:227]
	v_fma_f32 v70, |v216|, v196, v70
	v_fma_f32 v71, |v217|, v196, v71
	v_mfma_f32_16x16x32_f16 v[228:231], v[50:53], v[202:205], v[228:231]
	v_fma_f32 v72, |v218|, v196, v72
	v_fma_f32 v73, |v219|, v196, v73
	v_mfma_f32_16x16x32_f16 v[232:235], v[38:41], v[202:205], v[232:235]
	v_fma_f32 v66, |v220|, v196, v66
	v_fma_f32 v67, |v221|, v196, v67
	v_mfma_f32_16x16x32_f16 v[240:243], v[34:37], v[202:205], v[240:243]
	v_fma_f32 v68, |v222|, v196, v68
	v_fma_f32 v69, |v223|, v196, v69
	ds_read_b128 v[188:191], v112 offset:26624
	ds_read_b128 v[192:195], v112 offset:27648
	ds_read_b32 v196, v145 offset:832
	s_waitcnt lgkmcnt(3)
	v_mfma_f32_16x16x32_f16 v[208:211], v[58:61], v[178:181], 0
	v_fma_f32 v74, |v224|, v206, v74
	v_fma_f32 v75, |v225|, v206, v75
	v_mfma_f32_16x16x32_f16 v[212:215], v[62:65], v[178:181], 0
	v_fma_f32 v76, |v226|, v206, v76
	v_fma_f32 v77, |v227|, v206, v77
	v_mfma_f32_16x16x32_f16 v[216:219], v[46:49], v[178:181], 0
	v_fma_f32 v78, |v228|, v206, v78
	v_fma_f32 v79, |v229|, v206, v79
	v_mfma_f32_16x16x32_f16 v[220:223], v[42:45], v[178:181], 0
	v_fma_f32 v80, |v230|, v206, v80
	v_fma_f32 v81, |v231|, v206, v81
	v_mfma_f32_16x16x32_f16 v[208:211], v[54:57], v[182:185], v[208:211]
	v_fma_f32 v70, |v232|, v206, v70
	v_fma_f32 v71, |v233|, v206, v71
	v_mfma_f32_16x16x32_f16 v[212:215], v[50:53], v[182:185], v[212:215]
	v_fma_f32 v72, |v234|, v206, v72
	v_fma_f32 v73, |v235|, v206, v73
	v_mfma_f32_16x16x32_f16 v[216:219], v[38:41], v[182:185], v[216:219]
	v_fma_f32 v66, |v240|, v206, v66
	v_fma_f32 v67, |v241|, v206, v67
	v_mfma_f32_16x16x32_f16 v[220:223], v[34:37], v[182:185], v[220:223]
	v_fma_f32 v68, |v242|, v206, v68
	v_fma_f32 v69, |v243|, v206, v69
	ds_read_b128 v[198:201], v112 offset:28672
	ds_read_b128 v[202:205], v112 offset:29696
	ds_read_b32 v206, v145 offset:896
	s_waitcnt lgkmcnt(3)
	v_mfma_f32_16x16x32_f16 v[224:227], v[58:61], v[188:191], 0
	v_fma_f32 v74, |v208|, v186, v74
	v_fma_f32 v75, |v209|, v186, v75
	v_mfma_f32_16x16x32_f16 v[228:231], v[62:65], v[188:191], 0
	v_fma_f32 v76, |v210|, v186, v76
	v_fma_f32 v77, |v211|, v186, v77
	v_mfma_f32_16x16x32_f16 v[232:235], v[46:49], v[188:191], 0
	v_fma_f32 v78, |v212|, v186, v78
	v_fma_f32 v79, |v213|, v186, v79
	v_mfma_f32_16x16x32_f16 v[240:243], v[42:45], v[188:191], 0
	v_fma_f32 v80, |v214|, v186, v80
	v_fma_f32 v81, |v215|, v186, v81
	v_mfma_f32_16x16x32_f16 v[224:227], v[54:57], v[192:195], v[224:227]
	v_fma_f32 v70, |v216|, v186, v70
	v_fma_f32 v71, |v217|, v186, v71
	v_mfma_f32_16x16x32_f16 v[228:231], v[50:53], v[192:195], v[228:231]
	v_fma_f32 v72, |v218|, v186, v72
	v_fma_f32 v73, |v219|, v186, v73
	v_mfma_f32_16x16x32_f16 v[232:235], v[38:41], v[192:195], v[232:235]
	v_fma_f32 v66, |v220|, v186, v66
	v_fma_f32 v67, |v221|, v186, v67
	v_mfma_f32_16x16x32_f16 v[240:243], v[34:37], v[192:195], v[240:243]
	v_fma_f32 v68, |v222|, v186, v68
	v_fma_f32 v69, |v223|, v186, v69
	ds_read_b128 v[178:181], v112 offset:30720
	ds_read_b128 v[182:185], v112 offset:31744
	ds_read_b32 v186, v145 offset:960
	s_waitcnt lgkmcnt(3)
; __device__ __forceinline__ void dsa_unit(int wv, const Args& A, LAS unsigned char* lds, int s, int qt) {
;     ...
;             for (int hh = 0; hh < 16; ++hh) {
;                 const h16x8 q0 = __builtin_bit_cast(h16x8, Ql[(hh * 2) * 64 + lane]), q1 = __builtin_bit_cast(h16x8, Ql[(hh * 2 + 1) * 64 + lane]);
;                 const float wh = wql[hh * 16 + fr];
;                 f32x4 a[4];
; #pragma unroll
;                 for (int t = 0; t < 4; ++t) a[t] = __builtin_amdgcn_mfma_f32_16x16x32_f16(kc[t][0], q0, (f32x4){0.f, 0.f, 0.f, 0.f}, 0, 0, 0);
; #pragma unroll
;                 for (int t = 0; t < 4; ++t) a[t] = __builtin_amdgcn_mfma_f32_16x16x32_f16(kc[t][1], q1, a[t], 0, 0, 0);
; #pragma unroll
;                 for (int t = 0; t < 4; ++t)
; #pragma unroll
;                     for (int r = 0; r < 4; ++r) sc[t][r] += wh * fabsf(a[t][r]);
;             }
;             { const h16x8 q0 = __builtin_bit_cast(h16x8, Ql[32 * 64 + lane]), q1 = __builtin_bit_cast(h16x8, Ql[33 * 64 + lane]);
; #pragma unroll
;                 for (int t = 0; t < 4; ++t) { sc[t] = __builtin_amdgcn_mfma_f32_16x16x32_f16(kc[t][0], q0, sc[t], 0, 0, 0); sc[t] = __builtin_amdgcn_mfma_f32_16x16x32_f16(kc[t][1], q1, sc[t], 0, 0, 0); } }
;             int c = 0;
; #pragma unroll
;             for (int t = 0; t < 4; ++t)
; #pragma unroll
;                 for (int r = 0; r < 4; ++r) c += (sc[t][r] > th) ? 1 : 0;
;             if (c) { unsigned pos = __hip_atomic_fetch_add((unsigned*)(cnt + fr), (unsigned)c, __ATOMIC_RELAXED, __HIP_MEMORY_SCOPE_WORKGROUP);
; #pragma unroll
;                 for (int t = 0; t < 4; ++t)
; #pragma unroll
;                     for (int r = 0; r < 4; ++r) if (sc[t][r] > th) { if (pos < (unsigned)CAP) { cs[fr * CAP + pos] = f2ord(sc[t][r]); ci[fr * CAP + pos] = (unsigned short)((kt + t) * 16 + fq * 4 + r); } ++pos; } }
	v_mfma_f32_16x16x32_f16 v[208:211], v[58:61], v[198:201], 0
	v_fma_f32 v74, |v224|, v196, v74
	v_fma_f32 v75, |v225|, v196, v75
	v_mfma_f32_16x16x32_f16 v[212:215], v[62:65], v[198:201], 0
	v_fma_f32 v76, |v226|, v196, v76
	v_fma_f32 v77, |v227|, v196, v77
	v_mfma_f32_16x16x32_f16 v[216:219], v[46:49], v[198:201], 0
	v_fma_f32 v78, |v228|, v196, v78
	v_fma_f32 v79, |v229|, v196, v79
	v_mfma_f32_16x16x32_f16 v[220:223], v[42:45], v[198:201], 0
	v_fma_f32 v80, |v230|, v196, v80
	v_fma_f32 v81, |v231|, v196, v81
	v_mfma_f32_16x16x32_f16 v[208:211], v[54:57], v[202:205], v[208:211]
	v_fma_f32 v70, |v232|, v196, v70
	v_fma_f32 v71, |v233|, v196, v71
	v_mfma_f32_16x16x32_f16 v[212:215], v[50:53], v[202:205], v[212:215]
	v_fma_f32 v72, |v234|, v196, v72
	v_fma_f32 v73, |v235|, v196, v73
	v_mfma_f32_16x16x32_f16 v[216:219], v[38:41], v[202:205], v[216:219]
	v_fma_f32 v66, |v240|, v196, v66
	v_fma_f32 v67, |v241|, v196, v67
	v_mfma_f32_16x16x32_f16 v[220:223], v[34:37], v[202:205], v[220:223]
	v_fma_f32 v68, |v242|, v196, v68
	v_fma_f32 v69, |v243|, v196, v69
	ds_read_b128 v[146:149], v112 offset:32768
	ds_read_b128 v[158:161], v112 offset:33792
	s_waitcnt lgkmcnt(2)
	v_mfma_f32_16x16x32_f16 v[224:227], v[58:61], v[178:181], 0
	v_fma_f32 v74, |v208|, v206, v74
	v_fma_f32 v75, |v209|, v206, v75
	v_mfma_f32_16x16x32_f16 v[228:231], v[62:65], v[178:181], 0
	v_fma_f32 v76, |v210|, v206, v76
	v_fma_f32 v77, |v211|, v206, v77
	v_mfma_f32_16x16x32_f16 v[232:235], v[46:49], v[178:181], 0
	v_fma_f32 v78, |v212|, v206, v78
	v_fma_f32 v79, |v213|, v206, v79
	v_mfma_f32_16x16x32_f16 v[240:243], v[42:45], v[178:181], 0
	v_fma_f32 v80, |v214|, v206, v80
	v_fma_f32 v81, |v215|, v206, v81
	v_mfma_f32_16x16x32_f16 v[224:227], v[54:57], v[182:185], v[224:227]
	v_fma_f32 v70, |v216|, v206, v70
	v_fma_f32 v71, |v217|, v206, v71
	v_mfma_f32_16x16x32_f16 v[228:231], v[50:53], v[182:185], v[228:231]
	v_fma_f32 v72, |v218|, v206, v72
	v_fma_f32 v73, |v219|, v206, v73
	v_mfma_f32_16x16x32_f16 v[232:235], v[38:41], v[182:185], v[232:235]
	v_fma_f32 v66, |v220|, v206, v66
	v_fma_f32 v67, |v221|, v206, v67
	v_mfma_f32_16x16x32_f16 v[240:243], v[34:37], v[182:185], v[240:243]
	v_fma_f32 v68, |v222|, v206, v68
	v_fma_f32 v69, |v223|, v206, v69
	v_fma_f32 v74, |v224|, v186, v74
	v_fma_f32 v75, |v225|, v186, v75
	v_fma_f32 v76, |v226|, v186, v76
	v_fma_f32 v77, |v227|, v186, v77
	v_fma_f32 v78, |v228|, v186, v78
	v_fma_f32 v79, |v229|, v186, v79
	v_fma_f32 v80, |v230|, v186, v80
	v_fma_f32 v81, |v231|, v186, v81
	v_fma_f32 v70, |v232|, v186, v70
	v_fma_f32 v71, |v233|, v186, v71
	v_fma_f32 v72, |v234|, v186, v72
	v_fma_f32 v73, |v235|, v186, v73
	v_fma_f32 v66, |v240|, v186, v66
	v_fma_f32 v67, |v241|, v186, v67
	v_fma_f32 v68, |v242|, v186, v68
	v_fma_f32 v69, |v243|, v186, v69
	s_waitcnt lgkmcnt(0)
	v_mfma_f32_16x16x32_f16 v[58:61], v[58:61], v[146:149], v[74:77]
	v_mfma_f32_16x16x32_f16 v[62:65], v[62:65], v[146:149], v[78:81]
	v_mfma_f32_16x16x32_f16 v[54:57], v[54:57], v[158:161], v[58:61]
	v_mfma_f32_16x16x32_f16 v[46:49], v[46:49], v[146:149], v[70:73]
	v_mfma_f32_16x16x32_f16 v[50:53], v[50:53], v[158:161], v[62:65]
	s_nop 5
	v_cmp_gt_f32_e64 s[38:39], v55, v119
	v_cmp_gt_f32_e64 s[40:41], v54, v119
	v_cmp_gt_f32_e64 s[36:37], v56, v119
	v_mfma_f32_16x16x32_f16 v[42:45], v[42:45], v[146:149], v[66:69]
	v_cndmask_b32_e64 v58, 0, 1, s[38:39]
	v_cmp_gt_f32_e64 s[34:35], v57, v119
	v_cndmask_b32_e64 v59, 0, 1, s[36:37]
	v_mfma_f32_16x16x32_f16 v[38:41], v[38:41], v[158:161], v[46:49]
	v_cmp_gt_f32_e64 s[30:31], v50, v119
	v_addc_co_u32_e64 v58, vcc, 0, v58, s[40:41]
	v_mfma_f32_16x16x32_f16 v[34:37], v[34:37], v[158:161], v[42:45]
	v_addc_co_u32_e64 v58, vcc, v58, v59, s[34:35]
	v_cndmask_b32_e64 v59, 0, 1, s[30:31]
	v_cmp_gt_f32_e64 s[28:29], v51, v119
	v_cmp_gt_f32_e64 s[26:27], v52, v119
	v_cmp_gt_f32_e64 s[24:25], v53, v119
	v_addc_co_u32_e64 v58, vcc, v58, v59, s[28:29]
	v_cndmask_b32_e64 v46, 0, 1, s[26:27]
	v_cmp_gt_f32_e64 s[22:23], v38, v119
	v_addc_co_u32_e64 v46, vcc, v58, v46, s[24:25]
	s_nop 0
	v_cndmask_b32_e64 v42, 0, 1, s[22:23]
	v_cmp_gt_f32_e64 s[20:21], v39, v119
	v_cmp_gt_f32_e64 s[18:19], v40, v119
	v_cmp_gt_f32_e64 s[16:17], v41, v119
	v_addc_co_u32_e64 v42, vcc, v46, v42, s[20:21]
	v_cndmask_b32_e64 v43, 0, 1, s[18:19]
	v_cmp_gt_f32_e64 s[14:15], v34, v119
	v_addc_co_u32_e64 v42, vcc, v42, v43, s[16:17]
	s_nop 0
	v_cndmask_b32_e64 v43, 0, 1, s[14:15]
	v_cmp_gt_f32_e64 s[12:13], v35, v119
	v_cmp_gt_f32_e64 s[10:11], v36, v119
	s_nop 0
	v_addc_co_u32_e64 v42, vcc, v42, v43, s[12:13]
	v_cndmask_b32_e64 v43, 0, 1, s[10:11]
	v_cmp_gt_f32_e32 vcc, v37, v119
	s_nop 1
	v_addc_co_u32_e64 v42, s[42:43], v42, v43, vcc
	v_cmp_ne_u32_e64 s[42:43], 0, v42
	s_and_saveexec_b64 s[90:91], s[42:43]
	s_cbranch_execz .LBB0_1000
	ds_add_rtn_u32 v43, v110, v42
	v_lshl_or_b32 v42, s70, 4, v114
	s_and_saveexec_b64 s[42:43], s[40:41]
	s_cbranch_execz .LBB0_967
	s_waitcnt lgkmcnt(0)
	v_cmp_gt_u32_e64 s[40:41], s71, v43
	s_and_saveexec_b64 s[92:93], s[40:41]
	s_cbranch_execz .LBB0_941
	v_cmp_lt_i32_e64 s[40:41], -1, v54
	v_add_u32_e32 v45, v43, v113
	v_lshl_add_u32 v46, v45, 2, 0
	v_cndmask_b32_e64 v44, -1, v156, s[40:41]
	v_xor_b32_e32 v44, v44, v54
	ds_write_b32 v46, v44
	v_lshl_add_u32 v44, v45, 1, 0
	v_add_u32_e32 v44, 0x13000, v44
	ds_write_b16 v44, v42

; #define LAS __attribute__((address_space(3)))
; __device__ __forceinline__ void dsa_unit(int wv, const Args& A, LAS unsigned char* lds, int s, int qt) {
;     ...
;             for (int eb = 0; eb < n; eb += 64) {
;                 h16x2 a2[4][8];
; #pragma unroll
;                 for (int hh = 0; hh < 4; ++hh)
; #pragma unroll
;                     for (int d2 = 0; d2 < 8; ++d2) a2[hh][d2] = (h16x2){0, 0};
; #pragma unroll
;                 for (int e0 = 0; e0 < 64; e0 += 4) { const int e = eb + e0 + ksub; const int j_ = lst[e];
;                     const unsigned char* vp = (s < 2) ? ws + WS_VC8 + ((size_t)s * SEQ + j_) * 256 : (j_ < PAST ? ws + WS_CV8 + ((size_t)(s - 2) * PAST + j_) * 256 : ws + WS_VC8 + ((size_t)NP + (s - 2) * 64 + (j_ - PAST)) * 256);
;                     const u32x4 wv8 = *(const u32x4*)(vp + sl16 * 16);
;                     const h16x4 ph = *(const LAS h16x4*)(Pw + e * 8 + g * 4);
.LBB0_1471:
	v_mov_b32_e32 v14, 0
	v_add_u32_e32 v76, s0, v105
	s_mov_b32 s12, 0
	v_mov_b32_e32 v77, v106
	v_mov_b32_e32 v15, v14
	v_mov_b32_e32 v16, v14
	v_mov_b32_e32 v17, v14
	v_mov_b32_e32 v12, v14
	v_mov_b32_e32 v13, v14
	v_mov_b32_e32 v10, v14
	v_mov_b32_e32 v11, v14
	v_mov_b32_e32 v8, v14
	v_mov_b32_e32 v9, v14
	v_mov_b32_e32 v6, v14
	v_mov_b32_e32 v7, v14
	v_mov_b32_e32 v4, v14
	v_mov_b32_e32 v5, v14
	v_mov_b32_e32 v2, v14
	v_mov_b32_e32 v3, v14
	v_mov_b32_e32 v42, v14
	v_mov_b32_e32 v43, v14
	v_mov_b32_e32 v40, v14
	v_mov_b32_e32 v41, v14
	v_mov_b32_e32 v38, v14
	v_mov_b32_e32 v39, v14
	v_mov_b32_e32 v36, v14
	v_mov_b32_e32 v37, v14
	v_mov_b32_e32 v34, v14
	v_mov_b32_e32 v35, v14
	v_mov_b32_e32 v32, v14
	v_mov_b32_e32 v33, v14
	v_mov_b32_e32 v20, v14
	v_mov_b32_e32 v21, v14
	v_mov_b32_e32 v18, v14
	v_mov_b32_e32 v19, v14
	v_mov_b32_e32 v58, v14
	v_mov_b32_e32 v59, v14
	v_mov_b32_e32 v56, v14
	v_mov_b32_e32 v57, v14
	v_mov_b32_e32 v54, v14
	v_mov_b32_e32 v55, v14
	v_mov_b32_e32 v52, v14
	v_mov_b32_e32 v53, v14
	v_mov_b32_e32 v50, v14
	v_mov_b32_e32 v51, v14
	v_mov_b32_e32 v48, v14
	v_mov_b32_e32 v49, v14
	v_mov_b32_e32 v46, v14
	v_mov_b32_e32 v47, v14
	v_mov_b32_e32 v44, v14
	v_mov_b32_e32 v45, v14
	v_mov_b32_e32 v74, v14
	v_mov_b32_e32 v75, v14
	v_mov_b32_e32 v72, v14
	v_mov_b32_e32 v73, v14
	v_mov_b32_e32 v70, v14
	v_mov_b32_e32 v71, v14
	v_mov_b32_e32 v68, v14
	v_mov_b32_e32 v69, v14
	v_mov_b32_e32 v66, v14
	v_mov_b32_e32 v67, v14
	v_mov_b32_e32 v64, v14
	v_mov_b32_e32 v65, v14
	v_mov_b32_e32 v62, v14
	v_mov_b32_e32 v63, v14
	v_mov_b32_e32 v60, v14
	v_mov_b32_e32 v61, v14
	v_mbcnt_lo_u32_b32 v169, -1, 0
	v_mbcnt_hi_u32_b32 v169, -1, v169
	v_and_b32_e32 v169, 15, v169
	v_lshlrev_b32_e32 v169, 4, v169
	v_add_u32_e32 v168, 0x13000, v76
	ds_read_u16 v136, v168
	ds_read_u16 v137, v168 offset:8
	ds_read_u16 v138, v168 offset:16
	ds_read_u16 v139, v168 offset:24
	ds_read_u16 v140, v168 offset:32
	ds_read_u16 v141, v168 offset:40
	ds_read_u16 v142, v168 offset:48
	ds_read_u16 v143, v168 offset:56
	ds_read_u16 v144, v168 offset:64
	ds_read_u16 v145, v168 offset:72
	ds_read_u16 v146, v168 offset:80
	ds_read_u16 v147, v168 offset:88
	ds_read_u16 v148, v168 offset:96
	ds_read_u16 v149, v168 offset:104
	ds_read_u16 v178, v168 offset:112
	ds_read_u16 v179, v168 offset:120
	s_waitcnt lgkmcnt(0)
	v_add_lshl_u32 v136, s48, v136, 8
	v_add_u32_e32 v136, v169, v136
	v_add_lshl_u32 v137, s48, v137, 8
	v_add_u32_e32 v137, v169, v137
	v_add_lshl_u32 v138, s48, v138, 8
	v_add_u32_e32 v138, v169, v138
	v_add_lshl_u32 v139, s48, v139, 8
	v_add_u32_e32 v139, v169, v139
	v_add_lshl_u32 v140, s48, v140, 8
	v_add_u32_e32 v140, v169, v140
	v_add_lshl_u32 v141, s48, v141, 8
	v_add_u32_e32 v141, v169, v141
	v_add_lshl_u32 v142, s48, v142, 8
	v_add_u32_e32 v142, v169, v142
	v_add_lshl_u32 v143, s48, v143, 8
	v_add_u32_e32 v143, v169, v143
	v_add_lshl_u32 v144, s48, v144, 8
	v_add_u32_e32 v144, v169, v144
	v_add_lshl_u32 v145, s48, v145, 8
	v_add_u32_e32 v145, v169, v145
	v_add_lshl_u32 v146, s48, v146, 8
	v_add_u32_e32 v146, v169, v146
	v_add_lshl_u32 v147, s48, v147, 8
	v_add_u32_e32 v147, v169, v147
	v_add_lshl_u32 v148, s48, v148, 8
	v_add_u32_e32 v148, v169, v148
	v_add_lshl_u32 v149, s48, v149, 8
	v_add_u32_e32 v149, v169, v149
	v_add_lshl_u32 v178, s48, v178, 8
	v_add_u32_e32 v178, v169, v178
	v_add_lshl_u32 v179, s48, v179, 8
	v_add_u32_e32 v179, v169, v179
	global_load_dwordx4 v[160:163], v136, s[86:87]
	global_load_dwordx4 v[164:167], v137, s[86:87]
	global_load_dwordx4 v[180:183], v138, s[86:87]
	global_load_dwordx4 v[184:187], v139, s[86:87]
	global_load_dwordx4 v[188:191], v140, s[86:87]
	global_load_dwordx4 v[192:195], v141, s[86:87]
	global_load_dwordx4 v[196:199], v142, s[86:87]
	global_load_dwordx4 v[200:203], v143, s[86:87]
	global_load_dwordx4 v[204:207], v144, s[86:87]
	global_load_dwordx4 v[208:211], v145, s[86:87]
	global_load_dwordx4 v[212:215], v146, s[86:87]
	global_load_dwordx4 v[216:219], v147, s[86:87]
	global_load_dwordx4 v[220:223], v148, s[86:87]
	global_load_dwordx4 v[224:227], v149, s[86:87]
	global_load_dwordx4 v[228:231], v178, s[86:87]
	global_load_dwordx4 v[232:235], v179, s[86:87]
.LBB0_1472:
	v_add_u32_e32 v78, 0, v76
	v_add_u32_e32 v79, 0, v77
	s_add_i32 s12, s12, 64
	v_add_u32_e32 v76, 0x80, v76
	v_add_u32_e32 v77, 0x400, v77
	s_waitcnt lgkmcnt(0)
	v_add_u32_e32 v0, 0x1cc80, v79
	ds_read_b64 v[84:85], v0
	s_cmp_ge_i32 s12, s29
	s_cselect_b32 s98, 0, 0x80
	v_add_u32_e32 v168, s98, v168
	ds_read_u16 v136, v168
	ds_read_u16 v137, v168 offset:8
	ds_read_u16 v138, v168 offset:16
	ds_read_u16 v139, v168 offset:24
	ds_read_u16 v140, v168 offset:32
	ds_read_u16 v141, v168 offset:40
	ds_read_u16 v142, v168 offset:48
	ds_read_u16 v143, v168 offset:56
	ds_read_u16 v144, v168 offset:64
	ds_read_u16 v145, v168 offset:72
	ds_read_u16 v146, v168 offset:80
	ds_read_u16 v147, v168 offset:88
	ds_read_u16 v148, v168 offset:96
	ds_read_u16 v149, v168 offset:104
	ds_read_u16 v178, v168 offset:112
	ds_read_u16 v179, v168 offset:120
	s_waitcnt vmcnt(15)
	v_cvt_pk_f32_fp8_e32 v[86:87], v160
	v_cvt_pk_f16_f32 v0, v86, v87
	v_cvt_pk_f32_fp8_sdwa v[86:87], v160 src0_sel:WORD_1
	s_waitcnt lgkmcnt(0)
; #define LAS __attribute__((address_space(3)))
; __device__ __forceinline__ void dsa_unit(int wv, const Args& A, LAS unsigned char* lds, int s, int qt) {
;     ...
;                 for (int e0 = 0; e0 < 64; e0 += 4) { const int e = eb + e0 + ksub; const int j_ = lst[e];
;                     const unsigned char* vp = (s < 2) ? ws + WS_VC8 + ((size_t)s * SEQ + j_) * 256 : (j_ < PAST ? ws + WS_CV8 + ((size_t)(s - 2) * PAST + j_) * 256 : ws + WS_VC8 + ((size_t)NP + (s - 2) * 64 + (j_ - PAST)) * 256);
;                     const u32x4 wv8 = *(const u32x4*)(vp + sl16 * 16);
;                     const h16x4 ph = *(const LAS h16x4*)(Pw + e * 8 + g * 4);
;                     h16x2 v2[8];
; #pragma unroll
;                     for (int d2 = 0; d2 < 8; ++d2) { const f32x2 f2 = (d2 & 1) ? __builtin_amdgcn_cvt_pk_f32_fp8((int)wv8[d2 >> 1], true) : __builtin_amdgcn_cvt_pk_f32_fp8((int)wv8[d2 >> 1], false);
;                         v2[d2] = (h16x2){(h16)f2[0], (h16)f2[1]}; }
; #pragma unroll
;                     for (int hh = 0; hh < 4; ++hh) { const h16x2 pp = {ph[hh], ph[hh]};
; #pragma unroll
;                         for (int d2 = 0; d2 < 8; ++d2) a2[hh][d2] = __builtin_elementwise_fma(pp, v2[d2], a2[hh][d2]); } }
	v_pk_fma_f16 v91, v84, v0, 0 op_sel_hi:[0,1,1]
	v_pk_fma_f16 v112, v84, v0, 0 op_sel:[1,0,0]
	v_pk_fma_f16 v120, v85, v0, 0 op_sel_hi:[0,1,1]
	v_cvt_pk_f16_f32 v88, v86, v87
	v_cvt_pk_f32_fp8_e32 v[86:87], v161
	v_cvt_pk_f32_fp8_sdwa v[80:81], v161 src0_sel:WORD_1
	v_pk_fma_f16 v128, v85, v0, 0 op_sel:[1,0,0]
	v_cvt_pk_f16_f32 v86, v86, v87
	v_cvt_pk_f16_f32 v87, v80, v81
	v_cvt_pk_f32_fp8_e32 v[80:81], v162
	v_pk_fma_f16 v93, v84, v86, 0 op_sel_hi:[0,1,1]
	v_pk_fma_f16 v107, v84, v87, 0 op_sel_hi:[0,1,1]
	v_cvt_pk_f16_f32 v89, v80, v81
	v_cvt_pk_f32_fp8_sdwa v[80:81], v162 src0_sel:WORD_1
	v_pk_fma_f16 v114, v84, v86, 0 op_sel:[1,0,0]
	v_pk_fma_f16 v115, v84, v87, 0 op_sel:[1,0,0]
	v_cvt_pk_f16_f32 v82, v80, v81
	v_cvt_pk_f32_fp8_e32 v[80:81], v163
	v_pk_fma_f16 v109, v84, v82, 0 op_sel_hi:[0,1,1]
	v_pk_fma_f16 v117, v84, v82, 0 op_sel:[1,0,0]
	v_pk_fma_f16 v125, v85, v82, 0 op_sel_hi:[0,1,1]
	v_cvt_pk_f16_f32 v90, v80, v81
	v_cvt_pk_f32_fp8_sdwa v[80:81], v163 src0_sel:WORD_1
	v_add_lshl_u32 v136, s48, v136, 8
	v_add_u32_e32 v136, v169, v136
	global_load_dwordx4 v[160:163], v136, s[86:87]
	v_pk_fma_f16 v131, v85, v82, 0 op_sel:[1,0,0]
	v_pk_fma_f16 v122, v85, v86, 0 op_sel_hi:[0,1,1]
	v_pk_fma_f16 v123, v85, v87, 0 op_sel_hi:[0,1,1]
	v_cvt_pk_f16_f32 v80, v80, v81
	v_pk_fma_f16 v111, v84, v80, 0 op_sel_hi:[0,1,1]
	v_pk_fma_f16 v119, v84, v80, 0 op_sel:[1,0,0]
	v_pk_fma_f16 v127, v85, v80, 0 op_sel_hi:[0,1,1]
	v_pk_fma_f16 v132, v85, v80, 0 op_sel:[1,0,0]
	v_pk_fma_f16 v129, v85, v86, 0 op_sel:[1,0,0]
	v_pk_fma_f16 v130, v85, v87, 0 op_sel:[1,0,0]
	v_add_u32_e32 v0, 0x1ccc0, v79
	v_pk_fma_f16 v92, v84, v88, 0 op_sel_hi:[0,1,1]
	v_pk_fma_f16 v108, v84, v89, 0 op_sel_hi:[0,1,1]
	v_pk_fma_f16 v110, v84, v90, 0 op_sel_hi:[0,1,1]
	v_pk_fma_f16 v113, v84, v88, 0 op_sel:[1,0,0]
	v_pk_fma_f16 v116, v84, v89, 0 op_sel:[1,0,0]
	v_pk_fma_f16 v118, v84, v90, 0 op_sel:[1,0,0]
	v_pk_fma_f16 v121, v85, v88, 0 op_sel_hi:[0,1,1]
	v_pk_fma_f16 v124, v85, v89, 0 op_sel_hi:[0,1,1]
	v_pk_fma_f16 v126, v85, v90, 0 op_sel_hi:[0,1,1]
	v_pk_fma_f16 v88, v85, v88, 0 op_sel:[1,0,0]
	v_pk_fma_f16 v89, v85, v89, 0 op_sel:[1,0,0]
	v_pk_fma_f16 v90, v85, v90, 0 op_sel:[1,0,0]
	ds_read_b64 v[84:85], v0
	s_waitcnt vmcnt(15)
	v_cvt_pk_f32_fp8_e32 v[86:87], v164
	v_cvt_pk_f16_f32 v0, v86, v87
	v_cvt_pk_f32_fp8_sdwa v[86:87], v164 src0_sel:WORD_1
	s_waitcnt lgkmcnt(0)
	v_pk_fma_f16 v91, v84, v0, v91 op_sel_hi:[0,1,1]
	v_pk_fma_f16 v112, v84, v0, v112 op_sel:[1,0,0]
	v_pk_fma_f16 v120, v85, v0, v120 op_sel_hi:[0,1,1]
	v_cvt_pk_f16_f32 v133, v86, v87
	v_cvt_pk_f32_fp8_e32 v[86:87], v165
	v_cvt_pk_f32_fp8_sdwa v[80:81], v165 src0_sel:WORD_1
	v_pk_fma_f16 v128, v85, v0, v128 op_sel:[1,0,0]
	v_cvt_pk_f16_f32 v86, v86, v87
	v_cvt_pk_f16_f32 v87, v80, v81
	v_cvt_pk_f32_fp8_e32 v[80:81], v166
	v_pk_fma_f16 v93, v84, v86, v93 op_sel_hi:[0,1,1]
	v_pk_fma_f16 v107, v84, v87, v107 op_sel_hi:[0,1,1]
	v_cvt_pk_f16_f32 v134, v80, v81
	v_cvt_pk_f32_fp8_sdwa v[80:81], v166 src0_sel:WORD_1
	v_pk_fma_f16 v114, v84, v86, v114 op_sel:[1,0,0]
	v_pk_fma_f16 v115, v84, v87, v115 op_sel:[1,0,0]
	v_cvt_pk_f16_f32 v82, v80, v81
	v_cvt_pk_f32_fp8_e32 v[80:81], v167
	v_pk_fma_f16 v109, v84, v82, v109 op_sel_hi:[0,1,1]
	v_pk_fma_f16 v117, v84, v82, v117 op_sel:[1,0,0]
	v_pk_fma_f16 v125, v85, v82, v125 op_sel_hi:[0,1,1]
	v_cvt_pk_f16_f32 v135, v80, v81
	v_cvt_pk_f32_fp8_sdwa v[80:81], v167 src0_sel:WORD_1
	v_add_lshl_u32 v137, s48, v137, 8
	v_add_u32_e32 v137, v169, v137
	global_load_dwordx4 v[164:167], v137, s[86:87]
	v_pk_fma_f16 v131, v85, v82, v131 op_sel:[1,0,0]
	v_pk_fma_f16 v122, v85, v86, v122 op_sel_hi:[0,1,1]
	v_pk_fma_f16 v123, v85, v87, v123 op_sel_hi:[0,1,1]
	v_cvt_pk_f16_f32 v80, v80, v81
	v_pk_fma_f16 v111, v84, v80, v111 op_sel_hi:[0,1,1]
	v_pk_fma_f16 v119, v84, v80, v119 op_sel:[1,0,0]
	v_pk_fma_f16 v127, v85, v80, v127 op_sel_hi:[0,1,1]
	v_pk_fma_f16 v132, v85, v80, v132 op_sel:[1,0,0]
	v_pk_fma_f16 v129, v85, v86, v129 op_sel:[1,0,0]
	v_pk_fma_f16 v130, v85, v87, v130 op_sel:[1,0,0]
	v_add_u32_e32 v0, 0x1cd00, v79
	v_pk_fma_f16 v92, v84, v133, v92 op_sel_hi:[0,1,1]
	v_pk_fma_f16 v108, v84, v134, v108 op_sel_hi:[0,1,1]
	v_pk_fma_f16 v110, v84, v135, v110 op_sel_hi:[0,1,1]
	v_pk_fma_f16 v113, v84, v133, v113 op_sel:[1,0,0]
	v_pk_fma_f16 v116, v84, v134, v116 op_sel:[1,0,0]
	v_pk_fma_f16 v118, v84, v135, v118 op_sel:[1,0,0]
	v_pk_fma_f16 v121, v85, v133, v121 op_sel_hi:[0,1,1]
	v_pk_fma_f16 v124, v85, v134, v124 op_sel_hi:[0,1,1]
	v_pk_fma_f16 v126, v85, v135, v126 op_sel_hi:[0,1,1]
	v_pk_fma_f16 v88, v85, v133, v88 op_sel:[1,0,0]
	v_pk_fma_f16 v89, v85, v134, v89 op_sel:[1,0,0]
	v_pk_fma_f16 v90, v85, v135, v90 op_sel:[1,0,0]
	ds_read_b64 v[84:85], v0
	s_waitcnt vmcnt(15)
	v_cvt_pk_f32_fp8_e32 v[86:87], v180
	v_cvt_pk_f16_f32 v0, v86, v87
	v_cvt_pk_f32_fp8_sdwa v[86:87], v180 src0_sel:WORD_1
	s_waitcnt lgkmcnt(0)
; #define LAS __attribute__((address_space(3)))
; __device__ __forceinline__ void dsa_unit(int wv, const Args& A, LAS unsigned char* lds, int s, int qt) {
;     ...
;                 for (int e0 = 0; e0 < 64; e0 += 4) { const int e = eb + e0 + ksub; const int j_ = lst[e];
;                     const unsigned char* vp = (s < 2) ? ws + WS_VC8 + ((size_t)s * SEQ + j_) * 256 : (j_ < PAST ? ws + WS_CV8 + ((size_t)(s - 2) * PAST + j_) * 256 : ws + WS_VC8 + ((size_t)NP + (s - 2) * 64 + (j_ - PAST)) * 256);
;                     const u32x4 wv8 = *(const u32x4*)(vp + sl16 * 16);
;                     const h16x4 ph = *(const LAS h16x4*)(Pw + e * 8 + g * 4);
;                     h16x2 v2[8];
; #pragma unroll
;                     for (int d2 = 0; d2 < 8; ++d2) { const f32x2 f2 = (d2 & 1) ? __builtin_amdgcn_cvt_pk_f32_fp8((int)wv8[d2 >> 1], true) : __builtin_amdgcn_cvt_pk_f32_fp8((int)wv8[d2 >> 1], false);
;                         v2[d2] = (h16x2){(h16)f2[0], (h16)f2[1]}; }
; #pragma unroll
;                     for (int hh = 0; hh < 4; ++hh) { const h16x2 pp = {ph[hh], ph[hh]};
; #pragma unroll
;                         for (int d2 = 0; d2 < 8; ++d2) a2[hh][d2] = __builtin_elementwise_fma(pp, v2[d2], a2[hh][d2]); } }
	v_pk_fma_f16 v91, v84, v0, v91 op_sel_hi:[0,1,1]
	v_pk_fma_f16 v112, v84, v0, v112 op_sel:[1,0,0]
	v_pk_fma_f16 v120, v85, v0, v120 op_sel_hi:[0,1,1]
	v_cvt_pk_f16_f32 v133, v86, v87
	v_cvt_pk_f32_fp8_e32 v[86:87], v181
	v_cvt_pk_f32_fp8_sdwa v[80:81], v181 src0_sel:WORD_1
	v_pk_fma_f16 v128, v85, v0, v128 op_sel:[1,0,0]
	v_cvt_pk_f16_f32 v86, v86, v87
	v_cvt_pk_f16_f32 v87, v80, v81
	v_cvt_pk_f32_fp8_e32 v[80:81], v182
	v_pk_fma_f16 v93, v84, v86, v93 op_sel_hi:[0,1,1]
	v_pk_fma_f16 v107, v84, v87, v107 op_sel_hi:[0,1,1]
	v_cvt_pk_f16_f32 v134, v80, v81
	v_cvt_pk_f32_fp8_sdwa v[80:81], v182 src0_sel:WORD_1
	v_pk_fma_f16 v114, v84, v86, v114 op_sel:[1,0,0]
	v_pk_fma_f16 v115, v84, v87, v115 op_sel:[1,0,0]
	v_cvt_pk_f16_f32 v82, v80, v81
	v_cvt_pk_f32_fp8_e32 v[80:81], v183
	v_pk_fma_f16 v109, v84, v82, v109 op_sel_hi:[0,1,1]
	v_pk_fma_f16 v117, v84, v82, v117 op_sel:[1,0,0]
	v_pk_fma_f16 v125, v85, v82, v125 op_sel_hi:[0,1,1]
	v_cvt_pk_f16_f32 v135, v80, v81
	v_cvt_pk_f32_fp8_sdwa v[80:81], v183 src0_sel:WORD_1
	v_add_lshl_u32 v138, s48, v138, 8
	v_add_u32_e32 v138, v169, v138
	global_load_dwordx4 v[180:183], v138, s[86:87]
	v_pk_fma_f16 v131, v85, v82, v131 op_sel:[1,0,0]
	v_pk_fma_f16 v122, v85, v86, v122 op_sel_hi:[0,1,1]
	v_pk_fma_f16 v123, v85, v87, v123 op_sel_hi:[0,1,1]
	v_cvt_pk_f16_f32 v80, v80, v81
	v_pk_fma_f16 v111, v84, v80, v111 op_sel_hi:[0,1,1]
	v_pk_fma_f16 v119, v84, v80, v119 op_sel:[1,0,0]
	v_pk_fma_f16 v127, v85, v80, v127 op_sel_hi:[0,1,1]
	v_pk_fma_f16 v132, v85, v80, v132 op_sel:[1,0,0]
	v_pk_fma_f16 v129, v85, v86, v129 op_sel:[1,0,0]
	v_pk_fma_f16 v130, v85, v87, v130 op_sel:[1,0,0]
	v_add_u32_e32 v0, 0x1cd40, v79
	v_pk_fma_f16 v92, v84, v133, v92 op_sel_hi:[0,1,1]
	v_pk_fma_f16 v108, v84, v134, v108 op_sel_hi:[0,1,1]
	v_pk_fma_f16 v110, v84, v135, v110 op_sel_hi:[0,1,1]
	v_pk_fma_f16 v113, v84, v133, v113 op_sel:[1,0,0]
	v_pk_fma_f16 v116, v84, v134, v116 op_sel:[1,0,0]
	v_pk_fma_f16 v118, v84, v135, v118 op_sel:[1,0,0]
	v_pk_fma_f16 v121, v85, v133, v121 op_sel_hi:[0,1,1]
	v_pk_fma_f16 v124, v85, v134, v124 op_sel_hi:[0,1,1]
	v_pk_fma_f16 v126, v85, v135, v126 op_sel_hi:[0,1,1]
	v_pk_fma_f16 v88, v85, v133, v88 op_sel:[1,0,0]
	v_pk_fma_f16 v89, v85, v134, v89 op_sel:[1,0,0]
	v_pk_fma_f16 v90, v85, v135, v90 op_sel:[1,0,0]
	ds_read_b64 v[84:85], v0
	s_waitcnt vmcnt(15)
	v_cvt_pk_f32_fp8_e32 v[86:87], v184
	v_cvt_pk_f16_f32 v0, v86, v87
	v_cvt_pk_f32_fp8_sdwa v[86:87], v184 src0_sel:WORD_1
	s_waitcnt lgkmcnt(0)
	v_pk_fma_f16 v91, v84, v0, v91 op_sel_hi:[0,1,1]
	v_pk_fma_f16 v112, v84, v0, v112 op_sel:[1,0,0]
	v_pk_fma_f16 v120, v85, v0, v120 op_sel_hi:[0,1,1]
	v_cvt_pk_f16_f32 v133, v86, v87
	v_cvt_pk_f32_fp8_e32 v[86:87], v185
	v_cvt_pk_f32_fp8_sdwa v[80:81], v185 src0_sel:WORD_1
	v_pk_fma_f16 v128, v85, v0, v128 op_sel:[1,0,0]
	v_cvt_pk_f16_f32 v86, v86, v87
	v_cvt_pk_f16_f32 v87, v80, v81
	v_cvt_pk_f32_fp8_e32 v[80:81], v186
	v_pk_fma_f16 v93, v84, v86, v93 op_sel_hi:[0,1,1]
	v_pk_fma_f16 v107, v84, v87, v107 op_sel_hi:[0,1,1]
	v_cvt_pk_f16_f32 v134, v80, v81
	v_cvt_pk_f32_fp8_sdwa v[80:81], v186 src0_sel:WORD_1
	v_pk_fma_f16 v114, v84, v86, v114 op_sel:[1,0,0]
	v_pk_fma_f16 v115, v84, v87, v115 op_sel:[1,0,0]
	v_cvt_pk_f16_f32 v82, v80, v81
	v_cvt_pk_f32_fp8_e32 v[80:81], v187
	v_pk_fma_f16 v109, v84, v82, v109 op_sel_hi:[0,1,1]
	v_pk_fma_f16 v117, v84, v82, v117 op_sel:[1,0,0]
	v_pk_fma_f16 v125, v85, v82, v125 op_sel_hi:[0,1,1]
	v_cvt_pk_f16_f32 v135, v80, v81
	v_cvt_pk_f32_fp8_sdwa v[80:81], v187 src0_sel:WORD_1
	v_add_lshl_u32 v139, s48, v139, 8
	v_add_u32_e32 v139, v169, v139
	global_load_dwordx4 v[184:187], v139, s[86:87]
	v_pk_fma_f16 v131, v85, v82, v131 op_sel:[1,0,0]
	v_pk_fma_f16 v122, v85, v86, v122 op_sel_hi:[0,1,1]
	v_pk_fma_f16 v123, v85, v87, v123 op_sel_hi:[0,1,1]
	v_cvt_pk_f16_f32 v80, v80, v81
	v_pk_fma_f16 v111, v84, v80, v111 op_sel_hi:[0,1,1]
	v_pk_fma_f16 v119, v84, v80, v119 op_sel:[1,0,0]
	v_pk_fma_f16 v127, v85, v80, v127 op_sel_hi:[0,1,1]
	v_pk_fma_f16 v132, v85, v80, v132 op_sel:[1,0,0]
	v_pk_fma_f16 v129, v85, v86, v129 op_sel:[1,0,0]
	v_pk_fma_f16 v130, v85, v87, v130 op_sel:[1,0,0]
	v_add_u32_e32 v0, 0x1cd80, v79
	v_pk_fma_f16 v92, v84, v133, v92 op_sel_hi:[0,1,1]
	v_pk_fma_f16 v108, v84, v134, v108 op_sel_hi:[0,1,1]
	v_pk_fma_f16 v110, v84, v135, v110 op_sel_hi:[0,1,1]
	v_pk_fma_f16 v113, v84, v133, v113 op_sel:[1,0,0]
	v_pk_fma_f16 v116, v84, v134, v116 op_sel:[1,0,0]
	v_pk_fma_f16 v118, v84, v135, v118 op_sel:[1,0,0]
	v_pk_fma_f16 v121, v85, v133, v121 op_sel_hi:[0,1,1]
	v_pk_fma_f16 v124, v85, v134, v124 op_sel_hi:[0,1,1]
	v_pk_fma_f16 v126, v85, v135, v126 op_sel_hi:[0,1,1]
	v_pk_fma_f16 v88, v85, v133, v88 op_sel:[1,0,0]
	v_pk_fma_f16 v89, v85, v134, v89 op_sel:[1,0,0]
	v_pk_fma_f16 v90, v85, v135, v90 op_sel:[1,0,0]
	ds_read_b64 v[84:85], v0
	s_waitcnt vmcnt(15)
	v_cvt_pk_f32_fp8_e32 v[86:87], v188
	v_cvt_pk_f16_f32 v0, v86, v87
	v_cvt_pk_f32_fp8_sdwa v[86:87], v188 src0_sel:WORD_1
	s_waitcnt lgkmcnt(0)
; #define LAS __attribute__((address_space(3)))
; __device__ __forceinline__ void dsa_unit(int wv, const Args& A, LAS unsigned char* lds, int s, int qt) {
;     ...
;                 for (int e0 = 0; e0 < 64; e0 += 4) { const int e = eb + e0 + ksub; const int j_ = lst[e];
;                     const unsigned char* vp = (s < 2) ? ws + WS_VC8 + ((size_t)s * SEQ + j_) * 256 : (j_ < PAST ? ws + WS_CV8 + ((size_t)(s - 2) * PAST + j_) * 256 : ws + WS_VC8 + ((size_t)NP + (s - 2) * 64 + (j_ - PAST)) * 256);
;                     const u32x4 wv8 = *(const u32x4*)(vp + sl16 * 16);
;                     const h16x4 ph = *(const LAS h16x4*)(Pw + e * 8 + g * 4);
;                     h16x2 v2[8];
; #pragma unroll
;                     for (int d2 = 0; d2 < 8; ++d2) { const f32x2 f2 = (d2 & 1) ? __builtin_amdgcn_cvt_pk_f32_fp8((int)wv8[d2 >> 1], true) : __builtin_amdgcn_cvt_pk_f32_fp8((int)wv8[d2 >> 1], false);
;                         v2[d2] = (h16x2){(h16)f2[0], (h16)f2[1]}; }
; #pragma unroll
;                     for (int hh = 0; hh < 4; ++hh) { const h16x2 pp = {ph[hh], ph[hh]};
; #pragma unroll
;                         for (int d2 = 0; d2 < 8; ++d2) a2[hh][d2] = __builtin_elementwise_fma(pp, v2[d2], a2[hh][d2]); } }
	v_pk_fma_f16 v91, v84, v0, v91 op_sel_hi:[0,1,1]
	v_pk_fma_f16 v112, v84, v0, v112 op_sel:[1,0,0]
	v_pk_fma_f16 v120, v85, v0, v120 op_sel_hi:[0,1,1]
	v_cvt_pk_f16_f32 v133, v86, v87
	v_cvt_pk_f32_fp8_e32 v[86:87], v189
	v_cvt_pk_f32_fp8_sdwa v[80:81], v189 src0_sel:WORD_1
	v_pk_fma_f16 v128, v85, v0, v128 op_sel:[1,0,0]
	v_cvt_pk_f16_f32 v86, v86, v87
	v_cvt_pk_f16_f32 v87, v80, v81
	v_cvt_pk_f32_fp8_e32 v[80:81], v190
	v_pk_fma_f16 v93, v84, v86, v93 op_sel_hi:[0,1,1]
	v_pk_fma_f16 v107, v84, v87, v107 op_sel_hi:[0,1,1]
	v_cvt_pk_f16_f32 v134, v80, v81
	v_cvt_pk_f32_fp8_sdwa v[80:81], v190 src0_sel:WORD_1
	v_pk_fma_f16 v114, v84, v86, v114 op_sel:[1,0,0]
	v_pk_fma_f16 v115, v84, v87, v115 op_sel:[1,0,0]
	v_cvt_pk_f16_f32 v82, v80, v81
	v_cvt_pk_f32_fp8_e32 v[80:81], v191
	v_pk_fma_f16 v109, v84, v82, v109 op_sel_hi:[0,1,1]
	v_pk_fma_f16 v117, v84, v82, v117 op_sel:[1,0,0]
	v_pk_fma_f16 v125, v85, v82, v125 op_sel_hi:[0,1,1]
	v_cvt_pk_f16_f32 v135, v80, v81
	v_cvt_pk_f32_fp8_sdwa v[80:81], v191 src0_sel:WORD_1
	v_add_lshl_u32 v140, s48, v140, 8
	v_add_u32_e32 v140, v169, v140
	global_load_dwordx4 v[188:191], v140, s[86:87]
	v_pk_fma_f16 v131, v85, v82, v131 op_sel:[1,0,0]
	v_pk_fma_f16 v122, v85, v86, v122 op_sel_hi:[0,1,1]
	v_pk_fma_f16 v123, v85, v87, v123 op_sel_hi:[0,1,1]
	v_cvt_pk_f16_f32 v80, v80, v81
	v_pk_fma_f16 v111, v84, v80, v111 op_sel_hi:[0,1,1]
	v_pk_fma_f16 v119, v84, v80, v119 op_sel:[1,0,0]
	v_pk_fma_f16 v127, v85, v80, v127 op_sel_hi:[0,1,1]
	v_pk_fma_f16 v132, v85, v80, v132 op_sel:[1,0,0]
	v_pk_fma_f16 v129, v85, v86, v129 op_sel:[1,0,0]
	v_pk_fma_f16 v130, v85, v87, v130 op_sel:[1,0,0]
	v_add_u32_e32 v0, 0x1cdc0, v79
	v_pk_fma_f16 v92, v84, v133, v92 op_sel_hi:[0,1,1]
	v_pk_fma_f16 v108, v84, v134, v108 op_sel_hi:[0,1,1]
	v_pk_fma_f16 v110, v84, v135, v110 op_sel_hi:[0,1,1]
	v_pk_fma_f16 v113, v84, v133, v113 op_sel:[1,0,0]
	v_pk_fma_f16 v116, v84, v134, v116 op_sel:[1,0,0]
	v_pk_fma_f16 v118, v84, v135, v118 op_sel:[1,0,0]
	v_pk_fma_f16 v121, v85, v133, v121 op_sel_hi:[0,1,1]
	v_pk_fma_f16 v124, v85, v134, v124 op_sel_hi:[0,1,1]
	v_pk_fma_f16 v126, v85, v135, v126 op_sel_hi:[0,1,1]
	v_pk_fma_f16 v88, v85, v133, v88 op_sel:[1,0,0]
	v_pk_fma_f16 v89, v85, v134, v89 op_sel:[1,0,0]
	v_pk_fma_f16 v90, v85, v135, v90 op_sel:[1,0,0]
	ds_read_b64 v[84:85], v0
	s_waitcnt vmcnt(15)
	v_cvt_pk_f32_fp8_e32 v[86:87], v192
	v_cvt_pk_f16_f32 v0, v86, v87
	v_cvt_pk_f32_fp8_sdwa v[86:87], v192 src0_sel:WORD_1
	s_waitcnt lgkmcnt(0)
	v_pk_fma_f16 v91, v84, v0, v91 op_sel_hi:[0,1,1]
	v_pk_fma_f16 v112, v84, v0, v112 op_sel:[1,0,0]
	v_pk_fma_f16 v120, v85, v0, v120 op_sel_hi:[0,1,1]
	v_cvt_pk_f16_f32 v133, v86, v87
	v_cvt_pk_f32_fp8_e32 v[86:87], v193
	v_cvt_pk_f32_fp8_sdwa v[80:81], v193 src0_sel:WORD_1
	v_pk_fma_f16 v128, v85, v0, v128 op_sel:[1,0,0]
	v_cvt_pk_f16_f32 v86, v86, v87
	v_cvt_pk_f16_f32 v87, v80, v81
	v_cvt_pk_f32_fp8_e32 v[80:81], v194
	v_pk_fma_f16 v93, v84, v86, v93 op_sel_hi:[0,1,1]
	v_pk_fma_f16 v107, v84, v87, v107 op_sel_hi:[0,1,1]
	v_cvt_pk_f16_f32 v134, v80, v81
	v_cvt_pk_f32_fp8_sdwa v[80:81], v194 src0_sel:WORD_1
	v_pk_fma_f16 v114, v84, v86, v114 op_sel:[1,0,0]
	v_pk_fma_f16 v115, v84, v87, v115 op_sel:[1,0,0]
	v_cvt_pk_f16_f32 v82, v80, v81
	v_cvt_pk_f32_fp8_e32 v[80:81], v195
	v_pk_fma_f16 v109, v84, v82, v109 op_sel_hi:[0,1,1]
	v_pk_fma_f16 v117, v84, v82, v117 op_sel:[1,0,0]
	v_pk_fma_f16 v125, v85, v82, v125 op_sel_hi:[0,1,1]
	v_cvt_pk_f16_f32 v135, v80, v81
	v_cvt_pk_f32_fp8_sdwa v[80:81], v195 src0_sel:WORD_1
	v_add_lshl_u32 v141, s48, v141, 8
	v_add_u32_e32 v141, v169, v141
	global_load_dwordx4 v[192:195], v141, s[86:87]
	v_pk_fma_f16 v131, v85, v82, v131 op_sel:[1,0,0]
	v_pk_fma_f16 v122, v85, v86, v122 op_sel_hi:[0,1,1]
	v_pk_fma_f16 v123, v85, v87, v123 op_sel_hi:[0,1,1]
	v_cvt_pk_f16_f32 v80, v80, v81
	v_pk_fma_f16 v111, v84, v80, v111 op_sel_hi:[0,1,1]
	v_pk_fma_f16 v119, v84, v80, v119 op_sel:[1,0,0]
	v_pk_fma_f16 v127, v85, v80, v127 op_sel_hi:[0,1,1]
	v_pk_fma_f16 v132, v85, v80, v132 op_sel:[1,0,0]
	v_pk_fma_f16 v129, v85, v86, v129 op_sel:[1,0,0]
	v_pk_fma_f16 v130, v85, v87, v130 op_sel:[1,0,0]
	v_add_u32_e32 v0, 0x1ce00, v79
	v_pk_fma_f16 v92, v84, v133, v92 op_sel_hi:[0,1,1]
	v_pk_fma_f16 v108, v84, v134, v108 op_sel_hi:[0,1,1]
	v_pk_fma_f16 v110, v84, v135, v110 op_sel_hi:[0,1,1]
	v_pk_fma_f16 v113, v84, v133, v113 op_sel:[1,0,0]
	v_pk_fma_f16 v116, v84, v134, v116 op_sel:[1,0,0]
	v_pk_fma_f16 v118, v84, v135, v118 op_sel:[1,0,0]
	v_pk_fma_f16 v121, v85, v133, v121 op_sel_hi:[0,1,1]
	v_pk_fma_f16 v124, v85, v134, v124 op_sel_hi:[0,1,1]
	v_pk_fma_f16 v126, v85, v135, v126 op_sel_hi:[0,1,1]
	v_pk_fma_f16 v88, v85, v133, v88 op_sel:[1,0,0]
	v_pk_fma_f16 v89, v85, v134, v89 op_sel:[1,0,0]
	v_pk_fma_f16 v90, v85, v135, v90 op_sel:[1,0,0]
	ds_read_b64 v[84:85], v0
	s_waitcnt vmcnt(15)
	v_cvt_pk_f32_fp8_e32 v[86:87], v196
	v_cvt_pk_f16_f32 v0, v86, v87
	v_cvt_pk_f32_fp8_sdwa v[86:87], v196 src0_sel:WORD_1
	s_waitcnt lgkmcnt(0)
; #define LAS __attribute__((address_space(3)))
; __device__ __forceinline__ void dsa_unit(int wv, const Args& A, LAS unsigned char* lds, int s, int qt) {
;     ...
;                 for (int e0 = 0; e0 < 64; e0 += 4) { const int e = eb + e0 + ksub; const int j_ = lst[e];
;                     const unsigned char* vp = (s < 2) ? ws + WS_VC8 + ((size_t)s * SEQ + j_) * 256 : (j_ < PAST ? ws + WS_CV8 + ((size_t)(s - 2) * PAST + j_) * 256 : ws + WS_VC8 + ((size_t)NP + (s - 2) * 64 + (j_ - PAST)) * 256);
;                     const u32x4 wv8 = *(const u32x4*)(vp + sl16 * 16);
;                     const h16x4 ph = *(const LAS h16x4*)(Pw + e * 8 + g * 4);
;                     h16x2 v2[8];
; #pragma unroll
;                     for (int d2 = 0; d2 < 8; ++d2) { const f32x2 f2 = (d2 & 1) ? __builtin_amdgcn_cvt_pk_f32_fp8((int)wv8[d2 >> 1], true) : __builtin_amdgcn_cvt_pk_f32_fp8((int)wv8[d2 >> 1], false);
;                         v2[d2] = (h16x2){(h16)f2[0], (h16)f2[1]}; }
; #pragma unroll
;                     for (int hh = 0; hh < 4; ++hh) { const h16x2 pp = {ph[hh], ph[hh]};
; #pragma unroll
;                         for (int d2 = 0; d2 < 8; ++d2) a2[hh][d2] = __builtin_elementwise_fma(pp, v2[d2], a2[hh][d2]); } }
	v_pk_fma_f16 v91, v84, v0, v91 op_sel_hi:[0,1,1]
	v_pk_fma_f16 v112, v84, v0, v112 op_sel:[1,0,0]
	v_pk_fma_f16 v120, v85, v0, v120 op_sel_hi:[0,1,1]
	v_cvt_pk_f16_f32 v133, v86, v87
	v_cvt_pk_f32_fp8_e32 v[86:87], v197
	v_cvt_pk_f32_fp8_sdwa v[80:81], v197 src0_sel:WORD_1
	v_pk_fma_f16 v128, v85, v0, v128 op_sel:[1,0,0]
	v_cvt_pk_f16_f32 v86, v86, v87
	v_cvt_pk_f16_f32 v87, v80, v81
	v_cvt_pk_f32_fp8_e32 v[80:81], v198
	v_pk_fma_f16 v93, v84, v86, v93 op_sel_hi:[0,1,1]
	v_pk_fma_f16 v107, v84, v87, v107 op_sel_hi:[0,1,1]
	v_cvt_pk_f16_f32 v134, v80, v81
	v_cvt_pk_f32_fp8_sdwa v[80:81], v198 src0_sel:WORD_1
	v_pk_fma_f16 v114, v84, v86, v114 op_sel:[1,0,0]
	v_pk_fma_f16 v115, v84, v87, v115 op_sel:[1,0,0]
	v_cvt_pk_f16_f32 v82, v80, v81
	v_cvt_pk_f32_fp8_e32 v[80:81], v199
	v_pk_fma_f16 v109, v84, v82, v109 op_sel_hi:[0,1,1]
	v_pk_fma_f16 v117, v84, v82, v117 op_sel:[1,0,0]
	v_pk_fma_f16 v125, v85, v82, v125 op_sel_hi:[0,1,1]
	v_cvt_pk_f16_f32 v135, v80, v81
	v_cvt_pk_f32_fp8_sdwa v[80:81], v199 src0_sel:WORD_1
	v_add_lshl_u32 v142, s48, v142, 8
	v_add_u32_e32 v142, v169, v142
	global_load_dwordx4 v[196:199], v142, s[86:87]
	v_pk_fma_f16 v131, v85, v82, v131 op_sel:[1,0,0]
	v_pk_fma_f16 v122, v85, v86, v122 op_sel_hi:[0,1,1]
	v_pk_fma_f16 v123, v85, v87, v123 op_sel_hi:[0,1,1]
	v_cvt_pk_f16_f32 v80, v80, v81
	v_pk_fma_f16 v111, v84, v80, v111 op_sel_hi:[0,1,1]
	v_pk_fma_f16 v119, v84, v80, v119 op_sel:[1,0,0]
	v_pk_fma_f16 v127, v85, v80, v127 op_sel_hi:[0,1,1]
	v_pk_fma_f16 v132, v85, v80, v132 op_sel:[1,0,0]
	v_pk_fma_f16 v129, v85, v86, v129 op_sel:[1,0,0]
	v_pk_fma_f16 v130, v85, v87, v130 op_sel:[1,0,0]
	v_add_u32_e32 v0, 0x1ce40, v79
	v_pk_fma_f16 v92, v84, v133, v92 op_sel_hi:[0,1,1]
	v_pk_fma_f16 v108, v84, v134, v108 op_sel_hi:[0,1,1]
	v_pk_fma_f16 v110, v84, v135, v110 op_sel_hi:[0,1,1]
	v_pk_fma_f16 v113, v84, v133, v113 op_sel:[1,0,0]
	v_pk_fma_f16 v116, v84, v134, v116 op_sel:[1,0,0]
	v_pk_fma_f16 v118, v84, v135, v118 op_sel:[1,0,0]
	v_pk_fma_f16 v121, v85, v133, v121 op_sel_hi:[0,1,1]
	v_pk_fma_f16 v124, v85, v134, v124 op_sel_hi:[0,1,1]
	v_pk_fma_f16 v126, v85, v135, v126 op_sel_hi:[0,1,1]
	v_pk_fma_f16 v88, v85, v133, v88 op_sel:[1,0,0]
	v_pk_fma_f16 v89, v85, v134, v89 op_sel:[1,0,0]
	v_pk_fma_f16 v90, v85, v135, v90 op_sel:[1,0,0]
	ds_read_b64 v[84:85], v0
	s_waitcnt vmcnt(15)
	v_cvt_pk_f32_fp8_e32 v[86:87], v200
	v_cvt_pk_f16_f32 v0, v86, v87
	v_cvt_pk_f32_fp8_sdwa v[86:87], v200 src0_sel:WORD_1
	s_waitcnt lgkmcnt(0)
	v_pk_fma_f16 v91, v84, v0, v91 op_sel_hi:[0,1,1]
	v_pk_fma_f16 v112, v84, v0, v112 op_sel:[1,0,0]
	v_pk_fma_f16 v120, v85, v0, v120 op_sel_hi:[0,1,1]
	v_cvt_pk_f16_f32 v133, v86, v87
	v_cvt_pk_f32_fp8_e32 v[86:87], v201
	v_cvt_pk_f32_fp8_sdwa v[80:81], v201 src0_sel:WORD_1
	v_pk_fma_f16 v128, v85, v0, v128 op_sel:[1,0,0]
	v_cvt_pk_f16_f32 v86, v86, v87
	v_cvt_pk_f16_f32 v87, v80, v81
	v_cvt_pk_f32_fp8_e32 v[80:81], v202
	v_pk_fma_f16 v93, v84, v86, v93 op_sel_hi:[0,1,1]
	v_pk_fma_f16 v107, v84, v87, v107 op_sel_hi:[0,1,1]
	v_cvt_pk_f16_f32 v134, v80, v81
	v_cvt_pk_f32_fp8_sdwa v[80:81], v202 src0_sel:WORD_1
	v_pk_fma_f16 v114, v84, v86, v114 op_sel:[1,0,0]
	v_pk_fma_f16 v115, v84, v87, v115 op_sel:[1,0,0]
	v_cvt_pk_f16_f32 v82, v80, v81
	v_cvt_pk_f32_fp8_e32 v[80:81], v203
	v_pk_fma_f16 v109, v84, v82, v109 op_sel_hi:[0,1,1]
	v_pk_fma_f16 v117, v84, v82, v117 op_sel:[1,0,0]
	v_pk_fma_f16 v125, v85, v82, v125 op_sel_hi:[0,1,1]
	v_cvt_pk_f16_f32 v135, v80, v81
	v_cvt_pk_f32_fp8_sdwa v[80:81], v203 src0_sel:WORD_1
	v_add_lshl_u32 v143, s48, v143, 8
	v_add_u32_e32 v143, v169, v143
	global_load_dwordx4 v[200:203], v143, s[86:87]
	v_pk_fma_f16 v131, v85, v82, v131 op_sel:[1,0,0]
	v_pk_fma_f16 v122, v85, v86, v122 op_sel_hi:[0,1,1]
	v_pk_fma_f16 v123, v85, v87, v123 op_sel_hi:[0,1,1]
	v_cvt_pk_f16_f32 v80, v80, v81
	v_pk_fma_f16 v111, v84, v80, v111 op_sel_hi:[0,1,1]
	v_pk_fma_f16 v119, v84, v80, v119 op_sel:[1,0,0]
	v_pk_fma_f16 v127, v85, v80, v127 op_sel_hi:[0,1,1]
	v_pk_fma_f16 v132, v85, v80, v132 op_sel:[1,0,0]
	v_pk_fma_f16 v129, v85, v86, v129 op_sel:[1,0,0]
	v_pk_fma_f16 v130, v85, v87, v130 op_sel:[1,0,0]
	v_add_u32_e32 v0, 0x1ce80, v79
	v_pk_fma_f16 v92, v84, v133, v92 op_sel_hi:[0,1,1]
	v_pk_fma_f16 v108, v84, v134, v108 op_sel_hi:[0,1,1]
	v_pk_fma_f16 v110, v84, v135, v110 op_sel_hi:[0,1,1]
	v_pk_fma_f16 v113, v84, v133, v113 op_sel:[1,0,0]
	v_pk_fma_f16 v116, v84, v134, v116 op_sel:[1,0,0]
	v_pk_fma_f16 v118, v84, v135, v118 op_sel:[1,0,0]
	v_pk_fma_f16 v121, v85, v133, v121 op_sel_hi:[0,1,1]
	v_pk_fma_f16 v124, v85, v134, v124 op_sel_hi:[0,1,1]
	v_pk_fma_f16 v126, v85, v135, v126 op_sel_hi:[0,1,1]
	v_pk_fma_f16 v88, v85, v133, v88 op_sel:[1,0,0]
	v_pk_fma_f16 v89, v85, v134, v89 op_sel:[1,0,0]
	v_pk_fma_f16 v90, v85, v135, v90 op_sel:[1,0,0]
	ds_read_b64 v[84:85], v0
	s_waitcnt vmcnt(15)
	v_cvt_pk_f32_fp8_e32 v[86:87], v204
	v_cvt_pk_f16_f32 v0, v86, v87
	v_cvt_pk_f32_fp8_sdwa v[86:87], v204 src0_sel:WORD_1
	s_waitcnt lgkmcnt(0)
; #define LAS __attribute__((address_space(3)))
; __device__ __forceinline__ void dsa_unit(int wv, const Args& A, LAS unsigned char* lds, int s, int qt) {
;     ...
;                 for (int e0 = 0; e0 < 64; e0 += 4) { const int e = eb + e0 + ksub; const int j_ = lst[e];
;                     const unsigned char* vp = (s < 2) ? ws + WS_VC8 + ((size_t)s * SEQ + j_) * 256 : (j_ < PAST ? ws + WS_CV8 + ((size_t)(s - 2) * PAST + j_) * 256 : ws + WS_VC8 + ((size_t)NP + (s - 2) * 64 + (j_ - PAST)) * 256);
;                     const u32x4 wv8 = *(const u32x4*)(vp + sl16 * 16);
;                     const h16x4 ph = *(const LAS h16x4*)(Pw + e * 8 + g * 4);
;                     h16x2 v2[8];
; #pragma unroll
;                     for (int d2 = 0; d2 < 8; ++d2) { const f32x2 f2 = (d2 & 1) ? __builtin_amdgcn_cvt_pk_f32_fp8((int)wv8[d2 >> 1], true) : __builtin_amdgcn_cvt_pk_f32_fp8((int)wv8[d2 >> 1], false);
;                         v2[d2] = (h16x2){(h16)f2[0], (h16)f2[1]}; }
; #pragma unroll
;                     for (int hh = 0; hh < 4; ++hh) { const h16x2 pp = {ph[hh], ph[hh]};
; #pragma unroll
;                         for (int d2 = 0; d2 < 8; ++d2) a2[hh][d2] = __builtin_elementwise_fma(pp, v2[d2], a2[hh][d2]); } }
	v_pk_fma_f16 v91, v84, v0, v91 op_sel_hi:[0,1,1]
	v_pk_fma_f16 v112, v84, v0, v112 op_sel:[1,0,0]
	v_pk_fma_f16 v120, v85, v0, v120 op_sel_hi:[0,1,1]
	v_cvt_pk_f16_f32 v133, v86, v87
	v_cvt_pk_f32_fp8_e32 v[86:87], v205
	v_cvt_pk_f32_fp8_sdwa v[80:81], v205 src0_sel:WORD_1
	v_pk_fma_f16 v128, v85, v0, v128 op_sel:[1,0,0]
	v_cvt_pk_f16_f32 v86, v86, v87
	v_cvt_pk_f16_f32 v87, v80, v81
	v_cvt_pk_f32_fp8_e32 v[80:81], v206
	v_pk_fma_f16 v93, v84, v86, v93 op_sel_hi:[0,1,1]
	v_pk_fma_f16 v107, v84, v87, v107 op_sel_hi:[0,1,1]
	v_cvt_pk_f16_f32 v134, v80, v81
	v_cvt_pk_f32_fp8_sdwa v[80:81], v206 src0_sel:WORD_1
	v_pk_fma_f16 v114, v84, v86, v114 op_sel:[1,0,0]
	v_pk_fma_f16 v115, v84, v87, v115 op_sel:[1,0,0]
	v_cvt_pk_f16_f32 v82, v80, v81
	v_cvt_pk_f32_fp8_e32 v[80:81], v207
	v_pk_fma_f16 v109, v84, v82, v109 op_sel_hi:[0,1,1]
	v_pk_fma_f16 v117, v84, v82, v117 op_sel:[1,0,0]
	v_pk_fma_f16 v125, v85, v82, v125 op_sel_hi:[0,1,1]
	v_cvt_pk_f16_f32 v135, v80, v81
	v_cvt_pk_f32_fp8_sdwa v[80:81], v207 src0_sel:WORD_1
	v_add_lshl_u32 v144, s48, v144, 8
	v_add_u32_e32 v144, v169, v144
	global_load_dwordx4 v[204:207], v144, s[86:87]
	v_pk_fma_f16 v131, v85, v82, v131 op_sel:[1,0,0]
	v_pk_fma_f16 v122, v85, v86, v122 op_sel_hi:[0,1,1]
	v_pk_fma_f16 v123, v85, v87, v123 op_sel_hi:[0,1,1]
	v_cvt_pk_f16_f32 v80, v80, v81
	v_pk_fma_f16 v111, v84, v80, v111 op_sel_hi:[0,1,1]
	v_pk_fma_f16 v119, v84, v80, v119 op_sel:[1,0,0]
	v_pk_fma_f16 v127, v85, v80, v127 op_sel_hi:[0,1,1]
	v_pk_fma_f16 v132, v85, v80, v132 op_sel:[1,0,0]
	v_pk_fma_f16 v129, v85, v86, v129 op_sel:[1,0,0]
	v_pk_fma_f16 v130, v85, v87, v130 op_sel:[1,0,0]
	v_add_u32_e32 v0, 0x1cec0, v79
	v_pk_fma_f16 v92, v84, v133, v92 op_sel_hi:[0,1,1]
	v_pk_fma_f16 v108, v84, v134, v108 op_sel_hi:[0,1,1]
	v_pk_fma_f16 v110, v84, v135, v110 op_sel_hi:[0,1,1]
	v_pk_fma_f16 v113, v84, v133, v113 op_sel:[1,0,0]
	v_pk_fma_f16 v116, v84, v134, v116 op_sel:[1,0,0]
	v_pk_fma_f16 v118, v84, v135, v118 op_sel:[1,0,0]
	v_pk_fma_f16 v121, v85, v133, v121 op_sel_hi:[0,1,1]
	v_pk_fma_f16 v124, v85, v134, v124 op_sel_hi:[0,1,1]
	v_pk_fma_f16 v126, v85, v135, v126 op_sel_hi:[0,1,1]
	v_pk_fma_f16 v88, v85, v133, v88 op_sel:[1,0,0]
	v_pk_fma_f16 v89, v85, v134, v89 op_sel:[1,0,0]
	v_pk_fma_f16 v90, v85, v135, v90 op_sel:[1,0,0]
	ds_read_b64 v[84:85], v0
	s_waitcnt vmcnt(15)
	v_cvt_pk_f32_fp8_e32 v[86:87], v208
	v_cvt_pk_f16_f32 v0, v86, v87
	v_cvt_pk_f32_fp8_sdwa v[86:87], v208 src0_sel:WORD_1
	s_waitcnt lgkmcnt(0)
	v_pk_fma_f16 v91, v84, v0, v91 op_sel_hi:[0,1,1]
	v_pk_fma_f16 v112, v84, v0, v112 op_sel:[1,0,0]
	v_pk_fma_f16 v120, v85, v0, v120 op_sel_hi:[0,1,1]
	v_cvt_pk_f16_f32 v133, v86, v87
	v_cvt_pk_f32_fp8_e32 v[86:87], v209
	v_cvt_pk_f32_fp8_sdwa v[80:81], v209 src0_sel:WORD_1
	v_pk_fma_f16 v128, v85, v0, v128 op_sel:[1,0,0]
	v_cvt_pk_f16_f32 v86, v86, v87
	v_cvt_pk_f16_f32 v87, v80, v81
	v_cvt_pk_f32_fp8_e32 v[80:81], v210
	v_pk_fma_f16 v93, v84, v86, v93 op_sel_hi:[0,1,1]
	v_pk_fma_f16 v107, v84, v87, v107 op_sel_hi:[0,1,1]
	v_cvt_pk_f16_f32 v134, v80, v81
	v_cvt_pk_f32_fp8_sdwa v[80:81], v210 src0_sel:WORD_1
	v_pk_fma_f16 v114, v84, v86, v114 op_sel:[1,0,0]
	v_pk_fma_f16 v115, v84, v87, v115 op_sel:[1,0,0]
	v_cvt_pk_f16_f32 v82, v80, v81
	v_cvt_pk_f32_fp8_e32 v[80:81], v211
	v_pk_fma_f16 v109, v84, v82, v109 op_sel_hi:[0,1,1]
	v_pk_fma_f16 v117, v84, v82, v117 op_sel:[1,0,0]
	v_pk_fma_f16 v125, v85, v82, v125 op_sel_hi:[0,1,1]
	v_cvt_pk_f16_f32 v135, v80, v81
	v_cvt_pk_f32_fp8_sdwa v[80:81], v211 src0_sel:WORD_1
	v_add_lshl_u32 v145, s48, v145, 8
	v_add_u32_e32 v145, v169, v145
	global_load_dwordx4 v[208:211], v145, s[86:87]
	v_pk_fma_f16 v131, v85, v82, v131 op_sel:[1,0,0]
	v_pk_fma_f16 v122, v85, v86, v122 op_sel_hi:[0,1,1]
	v_pk_fma_f16 v123, v85, v87, v123 op_sel_hi:[0,1,1]
	v_cvt_pk_f16_f32 v80, v80, v81
	v_pk_fma_f16 v111, v84, v80, v111 op_sel_hi:[0,1,1]
	v_pk_fma_f16 v119, v84, v80, v119 op_sel:[1,0,0]
	v_pk_fma_f16 v127, v85, v80, v127 op_sel_hi:[0,1,1]
	v_pk_fma_f16 v132, v85, v80, v132 op_sel:[1,0,0]
	v_pk_fma_f16 v129, v85, v86, v129 op_sel:[1,0,0]
	v_pk_fma_f16 v130, v85, v87, v130 op_sel:[1,0,0]
	v_add_u32_e32 v0, 0x1cf00, v79
	v_pk_fma_f16 v92, v84, v133, v92 op_sel_hi:[0,1,1]
	v_pk_fma_f16 v108, v84, v134, v108 op_sel_hi:[0,1,1]
	v_pk_fma_f16 v110, v84, v135, v110 op_sel_hi:[0,1,1]
	v_pk_fma_f16 v113, v84, v133, v113 op_sel:[1,0,0]
	v_pk_fma_f16 v116, v84, v134, v116 op_sel:[1,0,0]
	v_pk_fma_f16 v118, v84, v135, v118 op_sel:[1,0,0]
	v_pk_fma_f16 v121, v85, v133, v121 op_sel_hi:[0,1,1]
	v_pk_fma_f16 v124, v85, v134, v124 op_sel_hi:[0,1,1]
	v_pk_fma_f16 v126, v85, v135, v126 op_sel_hi:[0,1,1]
	v_pk_fma_f16 v88, v85, v133, v88 op_sel:[1,0,0]
	v_pk_fma_f16 v89, v85, v134, v89 op_sel:[1,0,0]
	v_pk_fma_f16 v90, v85, v135, v90 op_sel:[1,0,0]
	ds_read_b64 v[84:85], v0
	s_waitcnt vmcnt(15)
	v_cvt_pk_f32_fp8_e32 v[86:87], v212
	v_cvt_pk_f16_f32 v0, v86, v87
	v_cvt_pk_f32_fp8_sdwa v[86:87], v212 src0_sel:WORD_1
	s_waitcnt lgkmcnt(0)
; #define LAS __attribute__((address_space(3)))
; __device__ __forceinline__ void dsa_unit(int wv, const Args& A, LAS unsigned char* lds, int s, int qt) {
;     ...
;                 for (int e0 = 0; e0 < 64; e0 += 4) { const int e = eb + e0 + ksub; const int j_ = lst[e];
;                     const unsigned char* vp = (s < 2) ? ws + WS_VC8 + ((size_t)s * SEQ + j_) * 256 : (j_ < PAST ? ws + WS_CV8 + ((size_t)(s - 2) * PAST + j_) * 256 : ws + WS_VC8 + ((size_t)NP + (s - 2) * 64 + (j_ - PAST)) * 256);
;                     const u32x4 wv8 = *(const u32x4*)(vp + sl16 * 16);
;                     const h16x4 ph = *(const LAS h16x4*)(Pw + e * 8 + g * 4);
;                     h16x2 v2[8];
; #pragma unroll
;                     for (int d2 = 0; d2 < 8; ++d2) { const f32x2 f2 = (d2 & 1) ? __builtin_amdgcn_cvt_pk_f32_fp8((int)wv8[d2 >> 1], true) : __builtin_amdgcn_cvt_pk_f32_fp8((int)wv8[d2 >> 1], false);
;                         v2[d2] = (h16x2){(h16)f2[0], (h16)f2[1]}; }
; #pragma unroll
;                     for (int hh = 0; hh < 4; ++hh) { const h16x2 pp = {ph[hh], ph[hh]};
; #pragma unroll
;                         for (int d2 = 0; d2 < 8; ++d2) a2[hh][d2] = __builtin_elementwise_fma(pp, v2[d2], a2[hh][d2]); } }
	v_pk_fma_f16 v91, v84, v0, v91 op_sel_hi:[0,1,1]
	v_pk_fma_f16 v112, v84, v0, v112 op_sel:[1,0,0]
	v_pk_fma_f16 v120, v85, v0, v120 op_sel_hi:[0,1,1]
	v_cvt_pk_f16_f32 v133, v86, v87
	v_cvt_pk_f32_fp8_e32 v[86:87], v213
	v_cvt_pk_f32_fp8_sdwa v[80:81], v213 src0_sel:WORD_1
	v_pk_fma_f16 v128, v85, v0, v128 op_sel:[1,0,0]
	v_cvt_pk_f16_f32 v86, v86, v87
	v_cvt_pk_f16_f32 v87, v80, v81
	v_cvt_pk_f32_fp8_e32 v[80:81], v214
	v_pk_fma_f16 v93, v84, v86, v93 op_sel_hi:[0,1,1]
	v_pk_fma_f16 v107, v84, v87, v107 op_sel_hi:[0,1,1]
	v_cvt_pk_f16_f32 v134, v80, v81
	v_cvt_pk_f32_fp8_sdwa v[80:81], v214 src0_sel:WORD_1
	v_pk_fma_f16 v114, v84, v86, v114 op_sel:[1,0,0]
	v_pk_fma_f16 v115, v84, v87, v115 op_sel:[1,0,0]
	v_cvt_pk_f16_f32 v82, v80, v81
	v_cvt_pk_f32_fp8_e32 v[80:81], v215
	v_pk_fma_f16 v109, v84, v82, v109 op_sel_hi:[0,1,1]
	v_pk_fma_f16 v117, v84, v82, v117 op_sel:[1,0,0]
	v_pk_fma_f16 v125, v85, v82, v125 op_sel_hi:[0,1,1]
	v_cvt_pk_f16_f32 v135, v80, v81
	v_cvt_pk_f32_fp8_sdwa v[80:81], v215 src0_sel:WORD_1
	v_add_lshl_u32 v146, s48, v146, 8
	v_add_u32_e32 v146, v169, v146
	global_load_dwordx4 v[212:215], v146, s[86:87]
	v_pk_fma_f16 v131, v85, v82, v131 op_sel:[1,0,0]
	v_pk_fma_f16 v122, v85, v86, v122 op_sel_hi:[0,1,1]
	v_pk_fma_f16 v123, v85, v87, v123 op_sel_hi:[0,1,1]
	v_cvt_pk_f16_f32 v80, v80, v81
	v_pk_fma_f16 v111, v84, v80, v111 op_sel_hi:[0,1,1]
	v_pk_fma_f16 v119, v84, v80, v119 op_sel:[1,0,0]
	v_pk_fma_f16 v127, v85, v80, v127 op_sel_hi:[0,1,1]
	v_pk_fma_f16 v132, v85, v80, v132 op_sel:[1,0,0]
	v_pk_fma_f16 v129, v85, v86, v129 op_sel:[1,0,0]
	v_pk_fma_f16 v130, v85, v87, v130 op_sel:[1,0,0]
	v_add_u32_e32 v0, 0x1cf40, v79
	v_pk_fma_f16 v92, v84, v133, v92 op_sel_hi:[0,1,1]
	v_pk_fma_f16 v108, v84, v134, v108 op_sel_hi:[0,1,1]
	v_pk_fma_f16 v110, v84, v135, v110 op_sel_hi:[0,1,1]
	v_pk_fma_f16 v113, v84, v133, v113 op_sel:[1,0,0]
	v_pk_fma_f16 v116, v84, v134, v116 op_sel:[1,0,0]
	v_pk_fma_f16 v118, v84, v135, v118 op_sel:[1,0,0]
	v_pk_fma_f16 v121, v85, v133, v121 op_sel_hi:[0,1,1]
	v_pk_fma_f16 v124, v85, v134, v124 op_sel_hi:[0,1,1]
	v_pk_fma_f16 v126, v85, v135, v126 op_sel_hi:[0,1,1]
	v_pk_fma_f16 v88, v85, v133, v88 op_sel:[1,0,0]
	v_pk_fma_f16 v89, v85, v134, v89 op_sel:[1,0,0]
	v_pk_fma_f16 v90, v85, v135, v90 op_sel:[1,0,0]
	ds_read_b64 v[84:85], v0
	s_waitcnt vmcnt(15)
	v_cvt_pk_f32_fp8_e32 v[86:87], v216
	v_cvt_pk_f16_f32 v0, v86, v87
	v_cvt_pk_f32_fp8_sdwa v[86:87], v216 src0_sel:WORD_1
	s_waitcnt lgkmcnt(0)
	v_pk_fma_f16 v91, v84, v0, v91 op_sel_hi:[0,1,1]
	v_pk_fma_f16 v112, v84, v0, v112 op_sel:[1,0,0]
	v_pk_fma_f16 v120, v85, v0, v120 op_sel_hi:[0,1,1]
	v_cvt_pk_f16_f32 v133, v86, v87
	v_cvt_pk_f32_fp8_e32 v[86:87], v217
	v_cvt_pk_f32_fp8_sdwa v[80:81], v217 src0_sel:WORD_1
	v_pk_fma_f16 v128, v85, v0, v128 op_sel:[1,0,0]
	v_cvt_pk_f16_f32 v86, v86, v87
	v_cvt_pk_f16_f32 v87, v80, v81
	v_cvt_pk_f32_fp8_e32 v[80:81], v218
	v_pk_fma_f16 v93, v84, v86, v93 op_sel_hi:[0,1,1]
	v_pk_fma_f16 v107, v84, v87, v107 op_sel_hi:[0,1,1]
	v_cvt_pk_f16_f32 v134, v80, v81
	v_cvt_pk_f32_fp8_sdwa v[80:81], v218 src0_sel:WORD_1
	v_pk_fma_f16 v114, v84, v86, v114 op_sel:[1,0,0]
	v_pk_fma_f16 v115, v84, v87, v115 op_sel:[1,0,0]
	v_cvt_pk_f16_f32 v82, v80, v81
	v_cvt_pk_f32_fp8_e32 v[80:81], v219
	v_pk_fma_f16 v109, v84, v82, v109 op_sel_hi:[0,1,1]
	v_pk_fma_f16 v117, v84, v82, v117 op_sel:[1,0,0]
	v_pk_fma_f16 v125, v85, v82, v125 op_sel_hi:[0,1,1]
	v_cvt_pk_f16_f32 v135, v80, v81
	v_cvt_pk_f32_fp8_sdwa v[80:81], v219 src0_sel:WORD_1
	v_add_lshl_u32 v147, s48, v147, 8
	v_add_u32_e32 v147, v169, v147
	global_load_dwordx4 v[216:219], v147, s[86:87]
	v_pk_fma_f16 v131, v85, v82, v131 op_sel:[1,0,0]
	v_pk_fma_f16 v122, v85, v86, v122 op_sel_hi:[0,1,1]
	v_pk_fma_f16 v123, v85, v87, v123 op_sel_hi:[0,1,1]
	v_cvt_pk_f16_f32 v80, v80, v81
	v_pk_fma_f16 v111, v84, v80, v111 op_sel_hi:[0,1,1]
	v_pk_fma_f16 v119, v84, v80, v119 op_sel:[1,0,0]
	v_pk_fma_f16 v127, v85, v80, v127 op_sel_hi:[0,1,1]
	v_pk_fma_f16 v132, v85, v80, v132 op_sel:[1,0,0]
	v_pk_fma_f16 v129, v85, v86, v129 op_sel:[1,0,0]
	v_pk_fma_f16 v130, v85, v87, v130 op_sel:[1,0,0]
	v_add_u32_e32 v0, 0x1cf80, v79
	v_pk_fma_f16 v92, v84, v133, v92 op_sel_hi:[0,1,1]
	v_pk_fma_f16 v108, v84, v134, v108 op_sel_hi:[0,1,1]
	v_pk_fma_f16 v110, v84, v135, v110 op_sel_hi:[0,1,1]
	v_pk_fma_f16 v113, v84, v133, v113 op_sel:[1,0,0]
	v_pk_fma_f16 v116, v84, v134, v116 op_sel:[1,0,0]
	v_pk_fma_f16 v118, v84, v135, v118 op_sel:[1,0,0]
	v_pk_fma_f16 v121, v85, v133, v121 op_sel_hi:[0,1,1]
	v_pk_fma_f16 v124, v85, v134, v124 op_sel_hi:[0,1,1]
	v_pk_fma_f16 v126, v85, v135, v126 op_sel_hi:[0,1,1]
	v_pk_fma_f16 v88, v85, v133, v88 op_sel:[1,0,0]
	v_pk_fma_f16 v89, v85, v134, v89 op_sel:[1,0,0]
	v_pk_fma_f16 v90, v85, v135, v90 op_sel:[1,0,0]
	ds_read_b64 v[84:85], v0
	s_waitcnt vmcnt(15)
	v_cvt_pk_f32_fp8_e32 v[86:87], v220
	v_cvt_pk_f16_f32 v0, v86, v87
	v_cvt_pk_f32_fp8_sdwa v[86:87], v220 src0_sel:WORD_1
	s_waitcnt lgkmcnt(0)
; #define LAS __attribute__((address_space(3)))
; __device__ __forceinline__ void dsa_unit(int wv, const Args& A, LAS unsigned char* lds, int s, int qt) {
;     ...
;                 for (int e0 = 0; e0 < 64; e0 += 4) { const int e = eb + e0 + ksub; const int j_ = lst[e];
;                     const unsigned char* vp = (s < 2) ? ws + WS_VC8 + ((size_t)s * SEQ + j_) * 256 : (j_ < PAST ? ws + WS_CV8 + ((size_t)(s - 2) * PAST + j_) * 256 : ws + WS_VC8 + ((size_t)NP + (s - 2) * 64 + (j_ - PAST)) * 256);
;                     const u32x4 wv8 = *(const u32x4*)(vp + sl16 * 16);
;                     const h16x4 ph = *(const LAS h16x4*)(Pw + e * 8 + g * 4);
;                     h16x2 v2[8];
; #pragma unroll
;                     for (int d2 = 0; d2 < 8; ++d2) { const f32x2 f2 = (d2 & 1) ? __builtin_amdgcn_cvt_pk_f32_fp8((int)wv8[d2 >> 1], true) : __builtin_amdgcn_cvt_pk_f32_fp8((int)wv8[d2 >> 1], false);
;                         v2[d2] = (h16x2){(h16)f2[0], (h16)f2[1]}; }
; #pragma unroll
;                     for (int hh = 0; hh < 4; ++hh) { const h16x2 pp = {ph[hh], ph[hh]};
; #pragma unroll
;                         for (int d2 = 0; d2 < 8; ++d2) a2[hh][d2] = __builtin_elementwise_fma(pp, v2[d2], a2[hh][d2]); } }
	v_pk_fma_f16 v91, v84, v0, v91 op_sel_hi:[0,1,1]
	v_pk_fma_f16 v112, v84, v0, v112 op_sel:[1,0,0]
	v_pk_fma_f16 v120, v85, v0, v120 op_sel_hi:[0,1,1]
	v_cvt_pk_f16_f32 v133, v86, v87
	v_cvt_pk_f32_fp8_e32 v[86:87], v221
	v_cvt_pk_f32_fp8_sdwa v[80:81], v221 src0_sel:WORD_1
	v_pk_fma_f16 v128, v85, v0, v128 op_sel:[1,0,0]
	v_cvt_pk_f16_f32 v86, v86, v87
	v_cvt_pk_f16_f32 v87, v80, v81
	v_cvt_pk_f32_fp8_e32 v[80:81], v222
	v_pk_fma_f16 v93, v84, v86, v93 op_sel_hi:[0,1,1]
	v_pk_fma_f16 v107, v84, v87, v107 op_sel_hi:[0,1,1]
	v_cvt_pk_f16_f32 v134, v80, v81
	v_cvt_pk_f32_fp8_sdwa v[80:81], v222 src0_sel:WORD_1
	v_pk_fma_f16 v114, v84, v86, v114 op_sel:[1,0,0]
	v_pk_fma_f16 v115, v84, v87, v115 op_sel:[1,0,0]
	v_cvt_pk_f16_f32 v82, v80, v81
	v_cvt_pk_f32_fp8_e32 v[80:81], v223
	v_pk_fma_f16 v109, v84, v82, v109 op_sel_hi:[0,1,1]
	v_pk_fma_f16 v117, v84, v82, v117 op_sel:[1,0,0]
	v_pk_fma_f16 v125, v85, v82, v125 op_sel_hi:[0,1,1]
	v_cvt_pk_f16_f32 v135, v80, v81
	v_cvt_pk_f32_fp8_sdwa v[80:81], v223 src0_sel:WORD_1
	v_add_lshl_u32 v148, s48, v148, 8
	v_add_u32_e32 v148, v169, v148
	global_load_dwordx4 v[220:223], v148, s[86:87]
	v_pk_fma_f16 v131, v85, v82, v131 op_sel:[1,0,0]
	v_pk_fma_f16 v122, v85, v86, v122 op_sel_hi:[0,1,1]
	v_pk_fma_f16 v123, v85, v87, v123 op_sel_hi:[0,1,1]
	v_cvt_pk_f16_f32 v80, v80, v81
	v_pk_fma_f16 v111, v84, v80, v111 op_sel_hi:[0,1,1]
	v_pk_fma_f16 v119, v84, v80, v119 op_sel:[1,0,0]
	v_pk_fma_f16 v127, v85, v80, v127 op_sel_hi:[0,1,1]
	v_pk_fma_f16 v132, v85, v80, v132 op_sel:[1,0,0]
	v_pk_fma_f16 v129, v85, v86, v129 op_sel:[1,0,0]
	v_pk_fma_f16 v130, v85, v87, v130 op_sel:[1,0,0]
	v_add_u32_e32 v0, 0x1cfc0, v79
	v_pk_fma_f16 v92, v84, v133, v92 op_sel_hi:[0,1,1]
	v_pk_fma_f16 v108, v84, v134, v108 op_sel_hi:[0,1,1]
	v_pk_fma_f16 v110, v84, v135, v110 op_sel_hi:[0,1,1]
	v_pk_fma_f16 v113, v84, v133, v113 op_sel:[1,0,0]
	v_pk_fma_f16 v116, v84, v134, v116 op_sel:[1,0,0]
	v_pk_fma_f16 v118, v84, v135, v118 op_sel:[1,0,0]
	v_pk_fma_f16 v121, v85, v133, v121 op_sel_hi:[0,1,1]
	v_pk_fma_f16 v124, v85, v134, v124 op_sel_hi:[0,1,1]
	v_pk_fma_f16 v126, v85, v135, v126 op_sel_hi:[0,1,1]
	v_pk_fma_f16 v88, v85, v133, v88 op_sel:[1,0,0]
	v_pk_fma_f16 v89, v85, v134, v89 op_sel:[1,0,0]
	v_pk_fma_f16 v90, v85, v135, v90 op_sel:[1,0,0]
	ds_read_b64 v[84:85], v0
	s_waitcnt vmcnt(15)
	v_cvt_pk_f32_fp8_e32 v[86:87], v224
	v_cvt_pk_f16_f32 v0, v86, v87
	v_cvt_pk_f32_fp8_sdwa v[86:87], v224 src0_sel:WORD_1
	s_waitcnt lgkmcnt(0)
	v_pk_fma_f16 v91, v84, v0, v91 op_sel_hi:[0,1,1]
	v_pk_fma_f16 v112, v84, v0, v112 op_sel:[1,0,0]
	v_pk_fma_f16 v120, v85, v0, v120 op_sel_hi:[0,1,1]
	v_cvt_pk_f16_f32 v133, v86, v87
	v_cvt_pk_f32_fp8_e32 v[86:87], v225
	v_cvt_pk_f32_fp8_sdwa v[80:81], v225 src0_sel:WORD_1
	v_pk_fma_f16 v128, v85, v0, v128 op_sel:[1,0,0]
	v_cvt_pk_f16_f32 v86, v86, v87
	v_cvt_pk_f16_f32 v87, v80, v81
	v_cvt_pk_f32_fp8_e32 v[80:81], v226
	v_pk_fma_f16 v93, v84, v86, v93 op_sel_hi:[0,1,1]
	v_pk_fma_f16 v107, v84, v87, v107 op_sel_hi:[0,1,1]
	v_cvt_pk_f16_f32 v134, v80, v81
	v_cvt_pk_f32_fp8_sdwa v[80:81], v226 src0_sel:WORD_1
	v_pk_fma_f16 v114, v84, v86, v114 op_sel:[1,0,0]
	v_pk_fma_f16 v115, v84, v87, v115 op_sel:[1,0,0]
	v_cvt_pk_f16_f32 v82, v80, v81
	v_cvt_pk_f32_fp8_e32 v[80:81], v227
	v_pk_fma_f16 v109, v84, v82, v109 op_sel_hi:[0,1,1]
	v_pk_fma_f16 v117, v84, v82, v117 op_sel:[1,0,0]
	v_pk_fma_f16 v125, v85, v82, v125 op_sel_hi:[0,1,1]
	v_cvt_pk_f16_f32 v135, v80, v81
	v_cvt_pk_f32_fp8_sdwa v[80:81], v227 src0_sel:WORD_1
	v_add_lshl_u32 v149, s48, v149, 8
	v_add_u32_e32 v149, v169, v149
	global_load_dwordx4 v[224:227], v149, s[86:87]
	v_pk_fma_f16 v131, v85, v82, v131 op_sel:[1,0,0]
	v_pk_fma_f16 v122, v85, v86, v122 op_sel_hi:[0,1,1]
	v_pk_fma_f16 v123, v85, v87, v123 op_sel_hi:[0,1,1]
	v_cvt_pk_f16_f32 v80, v80, v81
	v_pk_fma_f16 v111, v84, v80, v111 op_sel_hi:[0,1,1]
	v_pk_fma_f16 v119, v84, v80, v119 op_sel:[1,0,0]
	v_pk_fma_f16 v127, v85, v80, v127 op_sel_hi:[0,1,1]
	v_pk_fma_f16 v132, v85, v80, v132 op_sel:[1,0,0]
	v_pk_fma_f16 v129, v85, v86, v129 op_sel:[1,0,0]
	v_pk_fma_f16 v130, v85, v87, v130 op_sel:[1,0,0]
	v_add_u32_e32 v0, 0x1d000, v79
	v_pk_fma_f16 v92, v84, v133, v92 op_sel_hi:[0,1,1]
	v_pk_fma_f16 v108, v84, v134, v108 op_sel_hi:[0,1,1]
	v_pk_fma_f16 v110, v84, v135, v110 op_sel_hi:[0,1,1]
	v_pk_fma_f16 v113, v84, v133, v113 op_sel:[1,0,0]
	v_pk_fma_f16 v116, v84, v134, v116 op_sel:[1,0,0]
	v_pk_fma_f16 v118, v84, v135, v118 op_sel:[1,0,0]
	v_pk_fma_f16 v121, v85, v133, v121 op_sel_hi:[0,1,1]
	v_pk_fma_f16 v124, v85, v134, v124 op_sel_hi:[0,1,1]
	v_pk_fma_f16 v126, v85, v135, v126 op_sel_hi:[0,1,1]
	v_pk_fma_f16 v88, v85, v133, v88 op_sel:[1,0,0]
	v_pk_fma_f16 v89, v85, v134, v89 op_sel:[1,0,0]
	v_pk_fma_f16 v90, v85, v135, v90 op_sel:[1,0,0]
	ds_read_b64 v[84:85], v0
	s_waitcnt vmcnt(15)
	v_cvt_pk_f32_fp8_e32 v[86:87], v228
	v_cvt_pk_f16_f32 v0, v86, v87
	v_cvt_pk_f32_fp8_sdwa v[86:87], v228 src0_sel:WORD_1
	s_waitcnt lgkmcnt(0)
; #define LAS __attribute__((address_space(3)))
; __device__ __forceinline__ void dsa_unit(int wv, const Args& A, LAS unsigned char* lds, int s, int qt) {
;     ...
;                 for (int e0 = 0; e0 < 64; e0 += 4) { const int e = eb + e0 + ksub; const int j_ = lst[e];
;                     const unsigned char* vp = (s < 2) ? ws + WS_VC8 + ((size_t)s * SEQ + j_) * 256 : (j_ < PAST ? ws + WS_CV8 + ((size_t)(s - 2) * PAST + j_) * 256 : ws + WS_VC8 + ((size_t)NP + (s - 2) * 64 + (j_ - PAST)) * 256);
;                     const u32x4 wv8 = *(const u32x4*)(vp + sl16 * 16);
;                     const h16x4 ph = *(const LAS h16x4*)(Pw + e * 8 + g * 4);
;                     h16x2 v2[8];
; #pragma unroll
;                     for (int d2 = 0; d2 < 8; ++d2) { const f32x2 f2 = (d2 & 1) ? __builtin_amdgcn_cvt_pk_f32_fp8((int)wv8[d2 >> 1], true) : __builtin_amdgcn_cvt_pk_f32_fp8((int)wv8[d2 >> 1], false);
;                         v2[d2] = (h16x2){(h16)f2[0], (h16)f2[1]}; }
; #pragma unroll
;                     for (int hh = 0; hh < 4; ++hh) { const h16x2 pp = {ph[hh], ph[hh]};
; #pragma unroll
;                         for (int d2 = 0; d2 < 8; ++d2) a2[hh][d2] = __builtin_elementwise_fma(pp, v2[d2], a2[hh][d2]); } }
	v_pk_fma_f16 v91, v84, v0, v91 op_sel_hi:[0,1,1]
	v_pk_fma_f16 v112, v84, v0, v112 op_sel:[1,0,0]
	v_pk_fma_f16 v120, v85, v0, v120 op_sel_hi:[0,1,1]
	v_cvt_pk_f16_f32 v133, v86, v87
	v_cvt_pk_f32_fp8_e32 v[86:87], v229
	v_cvt_pk_f32_fp8_sdwa v[80:81], v229 src0_sel:WORD_1
	v_pk_fma_f16 v128, v85, v0, v128 op_sel:[1,0,0]
	v_cvt_pk_f16_f32 v86, v86, v87
	v_cvt_pk_f16_f32 v87, v80, v81
	v_cvt_pk_f32_fp8_e32 v[80:81], v230
	v_pk_fma_f16 v107, v84, v87, v107 op_sel_hi:[0,1,1]
	v_pk_fma_f16 v115, v84, v87, v115 op_sel:[1,0,0]
	v_cvt_pk_f16_f32 v134, v80, v81
	v_cvt_pk_f32_fp8_sdwa v[80:81], v230 src0_sel:WORD_1
	v_pk_fma_f16 v123, v85, v87, v123 op_sel_hi:[0,1,1]
	v_pk_fma_f16 v87, v85, v87, v130 op_sel:[1,0,0]
	v_cvt_pk_f16_f32 v82, v80, v81
	v_cvt_pk_f32_fp8_e32 v[80:81], v231
	v_pk_fma_f16 v93, v84, v86, v93 op_sel_hi:[0,1,1]
	v_pk_fma_f16 v109, v84, v82, v109 op_sel_hi:[0,1,1]
	v_pk_fma_f16 v114, v84, v86, v114 op_sel:[1,0,0]
	v_cvt_pk_f16_f32 v135, v80, v81
	v_cvt_pk_f32_fp8_sdwa v[80:81], v231 src0_sel:WORD_1
	v_add_lshl_u32 v178, s48, v178, 8
	v_add_u32_e32 v178, v169, v178
	global_load_dwordx4 v[228:231], v178, s[86:87]
	v_pk_fma_f16 v117, v84, v82, v117 op_sel:[1,0,0]
	v_pk_fma_f16 v122, v85, v86, v122 op_sel_hi:[0,1,1]
	v_pk_fma_f16 v125, v85, v82, v125 op_sel_hi:[0,1,1]
	v_cvt_pk_f16_f32 v80, v80, v81
	v_pk_fma_f16 v111, v84, v80, v111 op_sel_hi:[0,1,1]
	v_pk_fma_f16 v119, v84, v80, v119 op_sel:[1,0,0]
	v_pk_fma_f16 v127, v85, v80, v127 op_sel_hi:[0,1,1]
	v_pk_fma_f16 v130, v85, v80, v132 op_sel:[1,0,0]
	v_pk_fma_f16 v86, v85, v86, v129 op_sel:[1,0,0]
	v_pk_fma_f16 v129, v85, v82, v131 op_sel:[1,0,0]
	v_pk_fma_f16 v92, v84, v133, v92 op_sel_hi:[0,1,1]
	v_pk_fma_f16 v108, v84, v134, v108 op_sel_hi:[0,1,1]
	v_pk_fma_f16 v110, v84, v135, v110 op_sel_hi:[0,1,1]
	v_pk_fma_f16 v113, v84, v133, v113 op_sel:[1,0,0]
	v_pk_fma_f16 v116, v84, v134, v116 op_sel:[1,0,0]
	v_pk_fma_f16 v118, v84, v135, v118 op_sel:[1,0,0]
	v_pk_fma_f16 v121, v85, v133, v121 op_sel_hi:[0,1,1]
	v_pk_fma_f16 v124, v85, v134, v124 op_sel_hi:[0,1,1]
	v_pk_fma_f16 v126, v85, v135, v126 op_sel_hi:[0,1,1]
	v_pk_fma_f16 v88, v85, v133, v88 op_sel:[1,0,0]
	v_pk_fma_f16 v89, v85, v134, v89 op_sel:[1,0,0]
	v_pk_fma_f16 v90, v85, v135, v90 op_sel:[1,0,0]
	v_add_u32_e32 v0, 0x1d040, v79
	ds_read_b64 v[78:79], v0
	s_waitcnt vmcnt(15)
	v_cvt_pk_f32_fp8_e32 v[84:85], v232
	v_cvt_pk_f16_f32 v0, v84, v85
	v_cvt_pk_f32_fp8_sdwa v[84:85], v232 src0_sel:WORD_1
	v_cvt_pk_f16_f32 v131, v84, v85
	v_cvt_pk_f32_fp8_e32 v[84:85], v233
	v_cvt_pk_f32_fp8_sdwa v[80:81], v233 src0_sel:WORD_1
	s_waitcnt lgkmcnt(0)
	v_pk_fma_f16 v88, v79, v131, v88 op_sel:[1,0,0]
	v_cvt_pk_f16_f32 v84, v84, v85
	v_cvt_pk_f16_f32 v85, v80, v81
	v_cvt_pk_f32_fp8_e32 v[80:81], v234
	v_cvt_pk_f16_f32 v132, v80, v81
	v_cvt_pk_f32_fp8_sdwa v[80:81], v234 src0_sel:WORD_1
	v_cvt_pk_f16_f32 v82, v80, v81
	v_cvt_pk_f32_fp8_e32 v[80:81], v235
	v_cvt_pk_f16_f32 v133, v80, v81
	v_cvt_pk_f32_fp8_sdwa v[80:81], v235 src0_sel:WORD_1
	v_add_lshl_u32 v179, s48, v179, 8
	v_add_u32_e32 v179, v169, v179
	global_load_dwordx4 v[232:235], v179, s[86:87]
	v_pk_fma_f16 v83, v78, v131, v92 op_sel_hi:[0,1,1]
	v_pk_fma_f16 v92, v78, v85, v107 op_sel_hi:[0,1,1]
	v_pk_fma_f16 v107, v78, v82, v109 op_sel_hi:[0,1,1]
	v_cvt_pk_f16_f32 v80, v80, v81
	v_pk_fma_f16 v81, v78, v0, v91 op_sel_hi:[0,1,1]
	v_pk_fma_f16 v91, v78, v84, v93 op_sel_hi:[0,1,1]
	v_pk_fma_f16 v93, v78, v132, v108 op_sel_hi:[0,1,1]
	v_pk_fma_f16 v108, v78, v133, v110 op_sel_hi:[0,1,1]
	v_pk_fma_f16 v109, v78, v80, v111 op_sel_hi:[0,1,1]
	v_pk_fma_f16 v110, v78, v0, v112 op_sel:[1,0,0]
	v_pk_fma_f16 v111, v78, v131, v113 op_sel:[1,0,0]
	v_pk_fma_f16 v112, v78, v84, v114 op_sel:[1,0,0]
	v_pk_fma_f16 v113, v78, v85, v115 op_sel:[1,0,0]
	v_pk_fma_f16 v114, v78, v132, v116 op_sel:[1,0,0]
	v_pk_fma_f16 v115, v78, v82, v117 op_sel:[1,0,0]
	v_pk_fma_f16 v116, v78, v133, v118 op_sel:[1,0,0]
	v_pk_fma_f16 v117, v78, v80, v119 op_sel:[1,0,0]
	v_pk_fma_f16 v118, v79, v0, v120 op_sel_hi:[0,1,1]
	v_pk_fma_f16 v119, v79, v131, v121 op_sel_hi:[0,1,1]
	v_pk_fma_f16 v120, v79, v84, v122 op_sel_hi:[0,1,1]
	v_pk_fma_f16 v121, v79, v85, v123 op_sel_hi:[0,1,1]
	v_pk_fma_f16 v122, v79, v132, v124 op_sel_hi:[0,1,1]
	v_pk_fma_f16 v123, v79, v82, v125 op_sel_hi:[0,1,1]
	v_pk_fma_f16 v124, v79, v133, v126 op_sel_hi:[0,1,1]
	v_pk_fma_f16 v125, v79, v80, v127 op_sel_hi:[0,1,1]
	v_pk_fma_f16 v0, v79, v0, v128 op_sel:[1,0,0]
	v_pk_fma_f16 v84, v79, v84, v86 op_sel:[1,0,0]
	v_pk_fma_f16 v85, v79, v85, v87 op_sel:[1,0,0]
	v_pk_fma_f16 v86, v79, v132, v89 op_sel:[1,0,0]
	v_pk_fma_f16 v82, v79, v82, v129 op_sel:[1,0,0]
	v_pk_fma_f16 v87, v79, v133, v90 op_sel:[1,0,0]
	v_pk_fma_f16 v80, v79, v80, v130 op_sel:[1,0,0]
	v_cvt_f32_f16_e32 v78, v81
	v_cvt_f32_f16_sdwa v79, v81 dst_sel:DWORD dst_unused:UNUSED_PAD src0_sel:WORD_1
; __device__ __forceinline__ void dsa_unit(int wv, const Args& A, LAS unsigned char* lds, int s, int qt) {
;     ...
; #pragma unroll
;                 for (int hh = 0; hh < 4; ++hh)
; #pragma unroll
;                     for (int d2 = 0; d2 < 8; ++d2) { acc[hh][2 * d2] += (float)a2[hh][d2][0]; acc[hh][2 * d2 + 1] += (float)a2[hh][d2][1]; }
;             }
	v_pk_add_f32 v[74:75], v[74:75], v[78:79]
	v_cvt_f32_f16_e32 v78, v83
	v_cvt_f32_f16_sdwa v79, v83 dst_sel:DWORD dst_unused:UNUSED_PAD src0_sel:WORD_1
	v_pk_add_f32 v[72:73], v[72:73], v[78:79]
	v_cvt_f32_f16_e32 v78, v91
	v_cvt_f32_f16_sdwa v79, v91 dst_sel:DWORD dst_unused:UNUSED_PAD src0_sel:WORD_1
	v_pk_add_f32 v[70:71], v[70:71], v[78:79]
	v_cvt_f32_f16_e32 v78, v92
	v_cvt_f32_f16_sdwa v79, v92 dst_sel:DWORD dst_unused:UNUSED_PAD src0_sel:WORD_1
	v_pk_add_f32 v[68:69], v[68:69], v[78:79]
	v_cvt_f32_f16_e32 v78, v93
	v_cvt_f32_f16_sdwa v79, v93 dst_sel:DWORD dst_unused:UNUSED_PAD src0_sel:WORD_1
	v_pk_add_f32 v[66:67], v[66:67], v[78:79]
	v_cvt_f32_f16_e32 v78, v107
	v_cvt_f32_f16_sdwa v79, v107 dst_sel:DWORD dst_unused:UNUSED_PAD src0_sel:WORD_1
	v_pk_add_f32 v[64:65], v[64:65], v[78:79]
	v_cvt_f32_f16_e32 v78, v108
	v_cvt_f32_f16_sdwa v79, v108 dst_sel:DWORD dst_unused:UNUSED_PAD src0_sel:WORD_1
	v_pk_add_f32 v[62:63], v[62:63], v[78:79]
	v_cvt_f32_f16_e32 v78, v109
	v_cvt_f32_f16_sdwa v79, v109 dst_sel:DWORD dst_unused:UNUSED_PAD src0_sel:WORD_1
	v_pk_add_f32 v[60:61], v[60:61], v[78:79]
	v_cvt_f32_f16_e32 v78, v110
	v_cvt_f32_f16_sdwa v79, v110 dst_sel:DWORD dst_unused:UNUSED_PAD src0_sel:WORD_1
	v_pk_add_f32 v[58:59], v[58:59], v[78:79]
	v_cvt_f32_f16_e32 v78, v111
	v_cvt_f32_f16_sdwa v79, v111 dst_sel:DWORD dst_unused:UNUSED_PAD src0_sel:WORD_1
	v_pk_add_f32 v[56:57], v[56:57], v[78:79]
	v_cvt_f32_f16_e32 v78, v112
	v_cvt_f32_f16_sdwa v79, v112 dst_sel:DWORD dst_unused:UNUSED_PAD src0_sel:WORD_1
	v_pk_add_f32 v[54:55], v[54:55], v[78:79]
	v_cvt_f32_f16_e32 v78, v113
	v_cvt_f32_f16_sdwa v79, v113 dst_sel:DWORD dst_unused:UNUSED_PAD src0_sel:WORD_1
	v_pk_add_f32 v[52:53], v[52:53], v[78:79]
	v_cvt_f32_f16_e32 v78, v114
	v_cvt_f32_f16_sdwa v79, v114 dst_sel:DWORD dst_unused:UNUSED_PAD src0_sel:WORD_1
	v_pk_add_f32 v[50:51], v[50:51], v[78:79]
	v_cvt_f32_f16_e32 v78, v115
	v_cvt_f32_f16_sdwa v79, v115 dst_sel:DWORD dst_unused:UNUSED_PAD src0_sel:WORD_1
	v_pk_add_f32 v[48:49], v[48:49], v[78:79]
	v_cvt_f32_f16_e32 v78, v116
	v_cvt_f32_f16_sdwa v79, v116 dst_sel:DWORD dst_unused:UNUSED_PAD src0_sel:WORD_1
	v_pk_add_f32 v[46:47], v[46:47], v[78:79]
	v_cvt_f32_f16_e32 v78, v117
	v_cvt_f32_f16_sdwa v79, v117 dst_sel:DWORD dst_unused:UNUSED_PAD src0_sel:WORD_1
	v_pk_add_f32 v[44:45], v[44:45], v[78:79]
	v_cvt_f32_f16_e32 v78, v118
	v_cvt_f32_f16_sdwa v79, v118 dst_sel:DWORD dst_unused:UNUSED_PAD src0_sel:WORD_1
	v_pk_add_f32 v[42:43], v[42:43], v[78:79]
	v_cvt_f32_f16_e32 v78, v119
	v_cvt_f32_f16_sdwa v79, v119 dst_sel:DWORD dst_unused:UNUSED_PAD src0_sel:WORD_1
	v_pk_add_f32 v[40:41], v[40:41], v[78:79]
	v_cvt_f32_f16_e32 v78, v120
	v_cvt_f32_f16_sdwa v79, v120 dst_sel:DWORD dst_unused:UNUSED_PAD src0_sel:WORD_1
	v_pk_add_f32 v[38:39], v[38:39], v[78:79]
	v_cvt_f32_f16_e32 v78, v121
	v_cvt_f32_f16_sdwa v79, v121 dst_sel:DWORD dst_unused:UNUSED_PAD src0_sel:WORD_1
	v_pk_add_f32 v[36:37], v[36:37], v[78:79]
	v_cvt_f32_f16_e32 v78, v122
	v_cvt_f32_f16_sdwa v79, v122 dst_sel:DWORD dst_unused:UNUSED_PAD src0_sel:WORD_1
	v_pk_add_f32 v[34:35], v[34:35], v[78:79]
	v_cvt_f32_f16_e32 v78, v123
	v_cvt_f32_f16_sdwa v79, v123 dst_sel:DWORD dst_unused:UNUSED_PAD src0_sel:WORD_1
	v_pk_add_f32 v[32:33], v[32:33], v[78:79]
	v_cvt_f32_f16_e32 v78, v124
	v_cvt_f32_f16_sdwa v79, v124 dst_sel:DWORD dst_unused:UNUSED_PAD src0_sel:WORD_1
	v_pk_add_f32 v[20:21], v[20:21], v[78:79]
	v_cvt_f32_f16_e32 v78, v125
	v_cvt_f32_f16_sdwa v79, v125 dst_sel:DWORD dst_unused:UNUSED_PAD src0_sel:WORD_1
	v_pk_add_f32 v[18:19], v[18:19], v[78:79]
	v_cvt_f32_f16_e32 v78, v0
	v_cvt_f32_f16_sdwa v79, v0 dst_sel:DWORD dst_unused:UNUSED_PAD src0_sel:WORD_1
	v_pk_add_f32 v[14:15], v[14:15], v[78:79]
	v_cvt_f32_f16_e32 v78, v88
	v_cvt_f32_f16_sdwa v79, v88 dst_sel:DWORD dst_unused:UNUSED_PAD src0_sel:WORD_1
	v_pk_add_f32 v[16:17], v[16:17], v[78:79]
	v_cvt_f32_f16_e32 v78, v84
	v_cvt_f32_f16_sdwa v79, v84 dst_sel:DWORD dst_unused:UNUSED_PAD src0_sel:WORD_1
	v_pk_add_f32 v[12:13], v[12:13], v[78:79]
	v_cvt_f32_f16_e32 v78, v85
	v_cvt_f32_f16_sdwa v79, v85 dst_sel:DWORD dst_unused:UNUSED_PAD src0_sel:WORD_1
	v_pk_add_f32 v[10:11], v[10:11], v[78:79]
	v_cvt_f32_f16_e32 v78, v86
	v_cvt_f32_f16_sdwa v79, v86 dst_sel:DWORD dst_unused:UNUSED_PAD src0_sel:WORD_1
	v_pk_add_f32 v[8:9], v[8:9], v[78:79]
	v_cvt_f32_f16_e32 v78, v82
	v_cvt_f32_f16_sdwa v79, v82 dst_sel:DWORD dst_unused:UNUSED_PAD src0_sel:WORD_1
	v_pk_add_f32 v[6:7], v[6:7], v[78:79]
	v_cvt_f32_f16_e32 v78, v87
	v_cvt_f32_f16_sdwa v79, v87 dst_sel:DWORD dst_unused:UNUSED_PAD src0_sel:WORD_1
	v_pk_add_f32 v[4:5], v[4:5], v[78:79]
	v_cvt_f32_f16_e32 v78, v80
	v_cvt_f32_f16_sdwa v79, v80 dst_sel:DWORD dst_unused:UNUSED_PAD src0_sel:WORD_1
	v_pk_add_f32 v[2:3], v[2:3], v[78:79]
	s_cbranch_scc0 .LBB0_1472
	s_waitcnt vmcnt(0)
	s_branch .LBB0_1478

; __device__ __forceinline__ void dsa_unit(int wv, const Args& A, LAS unsigned char* lds, int s, int qt) {
;     ...
; #pragma unroll 2
;             for (int hh = 0; hh < 16; ++hh) {
;                 const h16x8 q0 = __builtin_bit_cast(h16x8, Ql[(hh * 2) * 64 + lane]), q1 = __builtin_bit_cast(h16x8, Ql[(hh * 2 + 1) * 64 + lane]);
;                 const float wh = wql[hh * 16 + fr];
;                 f32x4 a[4];
; #pragma unroll
;                 for (int t = 0; t < 4; ++t) a[t] = __builtin_amdgcn_mfma_f32_16x16x32_f16(kc[t][0], q0, (f32x4){0.f, 0.f, 0.f, 0.f}, 0, 0, 0);
; #pragma unroll
;                 for (int t = 0; t < 4; ++t) a[t] = __builtin_amdgcn_mfma_f32_16x16x32_f16(kc[t][1], q1, a[t], 0, 0, 0);
; #pragma unroll
;                 for (int t = 0; t < 4; ++t)
; #pragma unroll
;                     for (int r = 0; r < 4; ++r) sc[t][r] += wh * fabsf(a[t][r]);
;             }
;             { const h16x8 q0 = __builtin_bit_cast(h16x8, Ql[32 * 64 + lane]), q1 = __builtin_bit_cast(h16x8, Ql[33 * 64 + lane]);
; #pragma unroll
;                 for (int t = 0; t < 4; ++t) { sc[t] = __builtin_amdgcn_mfma_f32_16x16x32_f16(kc[t][0], q0, sc[t], 0, 0, 0); sc[t] = __builtin_amdgcn_mfma_f32_16x16x32_f16(kc[t][1], q1, sc[t], 0, 0, 0); } }
;             int c = 0;
; #pragma unroll
;             for (int t = 0; t < 4; ++t)
; #pragma unroll
;                 for (int r = 0; r < 4; ++r) c += (sc[t][r] > th) ? 1 : 0;
;             if (c) { unsigned pos = __hip_atomic_fetch_add((unsigned*)(cnt + fr), (unsigned)c, __ATOMIC_RELAXED, __HIP_MEMORY_SCOPE_WORKGROUP);
; #pragma unroll
;                 for (int t = 0; t < 4; ++t)
; #pragma unroll
;                     for (int r = 0; r < 4; ++r) if (sc[t][r] > th) { if (pos < (unsigned)CAP) { cs[fr * CAP + pos] = f2ord(sc[t][r]); ci[fr * CAP + pos] = (unsigned short)((kt + t) * 16 + fq * 4 + r); } ++pos; } }
.LBB0_1517:
	v_add_u32_e32 v123, 0, v122
	v_add_u32_e32 v124, 0x1cc80, v123
	ds_read_b128 v[124:127], v124
	v_add_u32_e32 v128, 0x1d080, v123
	v_add_u32_e32 v145, 0, v121
	ds_read_b128 v[128:131], v128
	v_add_u32_e32 v132, 0x25480, v145
	ds_read_b32 v144, v132
	s_waitcnt lgkmcnt(2)
	v_mfma_f32_16x16x32_f16 v[132:135], v[58:61], v[124:127], 0
	s_add_i32 s10, s10, -2
	v_add_u32_e32 v122, 0x1000, v122
	v_add_u32_e32 v121, 0x80, v121
	v_mfma_f32_16x16x32_f16 v[136:139], v[62:65], v[124:127], 0
	s_cmp_eq_u32 s10, 0
	v_mfma_f32_16x16x32_f16 v[140:143], v[50:53], v[124:127], 0
	v_mfma_f32_16x16x32_f16 v[124:127], v[46:49], v[124:127], 0
	s_waitcnt lgkmcnt(1)
	v_mfma_f32_16x16x32_f16 v[132:135], v[54:57], v[128:131], v[132:135]
	v_mfma_f32_16x16x32_f16 v[136:139], v[42:45], v[128:131], v[136:139]
	v_mfma_f32_16x16x32_f16 v[140:143], v[34:37], v[128:131], v[140:143]
	v_mfma_f32_16x16x32_f16 v[124:127], v[38:41], v[128:131], v[124:127]
	s_nop 4
	s_waitcnt lgkmcnt(0)
	v_fma_f32 v130, |v132|, v144, v74
	v_fma_f32 v131, |v133|, v144, v75
	v_fma_f32 v128, |v134|, v144, v76
	v_fma_f32 v129, |v135|, v144, v77
	v_fma_f32 v134, |v138|, v144, v80
	v_fma_f32 v135, |v139|, v144, v81
	v_fma_f32 v132, |v136|, v144, v78
	v_fma_f32 v133, |v137|, v144, v79
	v_fma_f32 v138, |v142|, v144, v72
	v_fma_f32 v139, |v143|, v144, v73
	v_fma_f32 v136, |v140|, v144, v70
	v_fma_f32 v137, |v141|, v144, v71
	v_fma_f32 v140, |v124|, v144, v66
	v_fma_f32 v141, |v125|, v144, v67
	v_add_u32_e32 v66, 0x1d480, v123
	v_fma_f32 v142, |v126|, v144, v68
	v_fma_f32 v143, |v127|, v144, v69
	ds_read_b128 v[66:69], v66
	v_add_u32_e32 v70, 0x1d880, v123
	ds_read_b128 v[70:73], v70
	v_add_u32_e32 v74, 0x254c0, v145
	ds_read_b32 v144, v74
	s_waitcnt lgkmcnt(2)
	v_mfma_f32_16x16x32_f16 v[74:77], v[58:61], v[66:69], 0
	v_mfma_f32_16x16x32_f16 v[78:81], v[62:65], v[66:69], 0
	v_mfma_f32_16x16x32_f16 v[124:127], v[50:53], v[66:69], 0
	v_mfma_f32_16x16x32_f16 v[66:69], v[46:49], v[66:69], 0
	s_waitcnt lgkmcnt(1)
	v_mfma_f32_16x16x32_f16 v[74:77], v[54:57], v[70:73], v[74:77]
	v_mfma_f32_16x16x32_f16 v[78:81], v[42:45], v[70:73], v[78:81]
	v_mfma_f32_16x16x32_f16 v[124:127], v[34:37], v[70:73], v[124:127]
	v_mfma_f32_16x16x32_f16 v[66:69], v[38:41], v[70:73], v[66:69]
	s_nop 4
	s_waitcnt lgkmcnt(0)
	v_fma_f32 v74, |v74|, v144, v130
	v_fma_f32 v75, |v75|, v144, v131
	v_fma_f32 v76, |v76|, v144, v128
	v_fma_f32 v77, |v77|, v144, v129
	v_fma_f32 v78, |v78|, v144, v132
	v_fma_f32 v79, |v79|, v144, v133
	v_fma_f32 v80, |v80|, v144, v134
	v_fma_f32 v81, |v81|, v144, v135
	v_fma_f32 v70, |v124|, v144, v136
	v_fma_f32 v71, |v125|, v144, v137
	v_fma_f32 v72, |v126|, v144, v138
	v_fma_f32 v73, |v127|, v144, v139
	v_fma_f32 v66, |v66|, v144, v140
	v_fma_f32 v67, |v67|, v144, v141
	v_fma_f32 v68, |v68|, v144, v142
	v_fma_f32 v69, |v69|, v144, v143
	s_cbranch_scc0 .LBB0_1517
	ds_read_b128 v[122:125], v112 offset:32768
	s_waitcnt lgkmcnt(0)
	v_mfma_f32_16x16x32_f16 v[58:61], v[58:61], v[122:125], v[74:77]
	s_nop 2
	ds_read_b128 v[74:77], v112 offset:33792
	v_mfma_f32_16x16x32_f16 v[62:65], v[62:65], v[122:125], v[78:81]
	s_waitcnt lgkmcnt(0)
	v_mfma_f32_16x16x32_f16 v[58:61], v[54:57], v[74:77], v[58:61]
	v_mfma_f32_16x16x32_f16 v[54:57], v[42:45], v[74:77], v[62:65]
	s_nop 6
	v_cmp_gt_f32_e64 s[38:39], v59, v120
	v_cmp_gt_f32_e64 s[40:41], v58, v120
	v_cmp_gt_f32_e64 s[36:37], v60, v120
	v_cndmask_b32_e64 v78, 0, 1, s[38:39]
	v_cmp_gt_f32_e64 s[34:35], v61, v120
	v_cndmask_b32_e64 v79, 0, 1, s[36:37]
	v_addc_co_u32_e64 v42, vcc, 0, v78, s[40:41]
	v_addc_co_u32_e64 v62, vcc, v42, v79, s[34:35]
	v_mfma_f32_16x16x32_f16 v[42:45], v[50:53], v[122:125], v[70:73]
	v_cmp_gt_f32_e64 s[30:31], v54, v120
	v_cmp_gt_f32_e64 s[28:29], v55, v120
	v_cmp_gt_f32_e64 s[26:27], v56, v120
	v_mfma_f32_16x16x32_f16 v[42:45], v[34:37], v[74:77], v[42:45]
	v_cndmask_b32_e64 v63, 0, 1, s[30:31]
	v_addc_co_u32_e64 v50, vcc, v62, v63, s[28:29]
	v_mfma_f32_16x16x32_f16 v[34:37], v[46:49], v[122:125], v[66:69]
	v_cndmask_b32_e64 v51, 0, 1, s[26:27]
	v_cmp_gt_f32_e64 s[24:25], v57, v120
	s_nop 2
	v_cmp_gt_f32_e64 s[22:23], v42, v120
	v_mfma_f32_16x16x32_f16 v[34:37], v[38:41], v[74:77], v[34:37]
	v_addc_co_u32_e64 v46, vcc, v50, v51, s[24:25]
	v_cndmask_b32_e64 v38, 0, 1, s[22:23]
	v_cmp_gt_f32_e64 s[20:21], v43, v120
	v_cmp_gt_f32_e64 s[18:19], v44, v120
	v_cmp_gt_f32_e64 s[16:17], v45, v120
	v_addc_co_u32_e64 v38, vcc, v46, v38, s[20:21]
	v_cndmask_b32_e64 v39, 0, 1, s[18:19]
	s_nop 0
	v_cmp_gt_f32_e64 s[14:15], v34, v120
	v_addc_co_u32_e64 v38, vcc, v38, v39, s[16:17]
	s_nop 0
	v_cndmask_b32_e64 v39, 0, 1, s[14:15]
	v_cmp_gt_f32_e64 s[12:13], v35, v120
	v_cmp_gt_f32_e64 s[10:11], v36, v120
	s_nop 0
	v_addc_co_u32_e64 v38, vcc, v38, v39, s[12:13]
	v_cndmask_b32_e64 v39, 0, 1, s[10:11]
	v_cmp_gt_f32_e32 vcc, v37, v120
	s_nop 1
	v_addc_co_u32_e64 v38, s[42:43], v38, v39, vcc
	v_cmp_ne_u32_e64 s[42:43], 0, v38
	s_and_saveexec_b64 s[92:93], s[42:43]
	s_cbranch_execz .LBB0_1581
	ds_add_rtn_u32 v39, v110, v38
	v_lshl_or_b32 v38, s94, 4, v114
	s_and_saveexec_b64 s[42:43], s[40:41]
	s_cbranch_execz .LBB0_1548
	s_waitcnt lgkmcnt(0)
	v_cmp_gt_u32_e64 s[40:41], s71, v39
	s_and_saveexec_b64 s[94:95], s[40:41]
	s_cbranch_execz .LBB0_1522
	v_cmp_lt_i32_e64 s[40:41], -1, v58
	v_add_u32_e32 v41, v39, v113
	v_lshl_add_u32 v46, v41, 2, 0
	v_cndmask_b32_e64 v40, -1, v156, s[40:41]
	v_xor_b32_e32 v40, v40, v58
	ds_write_b32 v46, v40
	v_lshl_add_u32 v40, v41, 1, 0
	v_add_u32_e32 v40, 0x13000, v40
	ds_write_b16 v40, v38

; #define LAS __attribute__((address_space(3)))
; __global__ void __launch_bounds__(512, 2) fwd_mega(Args A) {
;     extern __shared__ __attribute__((aligned(16))) unsigned char lds_raw[];
;     LAS unsigned char* lds = (LAS unsigned char*)lds_raw;
;     cg::grid_group grid = cg::this_grid();
;     const int wv = __builtin_amdgcn_readfirstlane((int)threadIdx.x >> 6);
	.amdhsa_kernel _Z8fwd_mega4Args
		.amdhsa_group_segment_fixed_size 0
		.amdhsa_private_segment_fixed_size 0
		.amdhsa_kernarg_size 488
		.amdhsa_user_sgpr_count 2
		.amdhsa_user_sgpr_dispatch_ptr 0
		.amdhsa_user_sgpr_queue_ptr 0
		.amdhsa_user_sgpr_kernarg_segment_ptr 1
		.amdhsa_user_sgpr_dispatch_id 0
		.amdhsa_user_sgpr_kernarg_preload_length 0
		.amdhsa_user_sgpr_kernarg_preload_offset 0
		.amdhsa_user_sgpr_private_segment_size 0
		.amdhsa_uses_dynamic_stack 0
		.amdhsa_enable_private_segment 0
		.amdhsa_system_sgpr_workgroup_id_x 1
		.amdhsa_system_sgpr_workgroup_id_y 0
		.amdhsa_system_sgpr_workgroup_id_z 0
		.amdhsa_system_sgpr_workgroup_info 0
		.amdhsa_system_vgpr_workitem_id 2
		.amdhsa_next_free_vgpr 256
		.amdhsa_next_free_sgpr 102
		.amdhsa_accum_offset 256
		.amdhsa_reserve_vcc 1
		.amdhsa_float_round_mode_32 0
		.amdhsa_float_round_mode_16_64 0
		.amdhsa_float_denorm_mode_32 3
		.amdhsa_float_denorm_mode_16_64 3
		.amdhsa_dx10_clamp 1
		.amdhsa_ieee_mode 1
		.amdhsa_fp16_overflow 0
		.amdhsa_tg_split 0
		.amdhsa_exception_fp_ieee_invalid_op 0
		.amdhsa_exception_fp_denorm_src 0
		.amdhsa_exception_fp_ieee_div_zero 0
		.amdhsa_exception_fp_ieee_overflow 0
		.amdhsa_exception_fp_ieee_underflow 0
		.amdhsa_exception_fp_ieee_inexact 0
		.amdhsa_exception_int_div_zero 0
	.end_amdhsa_kernel

; #define LAS __attribute__((address_space(3)))
; __global__ void __launch_bounds__(512, 2) fwd_mega(Args A) {
;     extern __shared__ __attribute__((aligned(16))) unsigned char lds_raw[];
;     LAS unsigned char* lds = (LAS unsigned char*)lds_raw;
;     cg::grid_group grid = cg::this_grid();
;     const int wv = __builtin_amdgcn_readfirstlane((int)threadIdx.x >> 6);
amdhsa.kernels:
  - .agpr_count:     0
    .args:
      - .offset:         0
        .size:           232
        .value_kind:     by_value
      - .offset:         232
        .size:           4
        .value_kind:     hidden_block_count_x
      - .offset:         236
        .size:           4
        .value_kind:     hidden_block_count_y
      - .offset:         240
        .size:           4
        .value_kind:     hidden_block_count_z
      - .offset:         244
        .size:           2
        .value_kind:     hidden_group_size_x
      - .offset:         246
        .size:           2
        .value_kind:     hidden_group_size_y
      - .offset:         248
        .size:           2
        .value_kind:     hidden_group_size_z
      - .offset:         250
        .size:           2
        .value_kind:     hidden_remainder_x
      - .offset:         252
        .size:           2
        .value_kind:     hidden_remainder_y
      - .offset:         254
        .size:           2
        .value_kind:     hidden_remainder_z
      - .offset:         272
        .size:           8
        .value_kind:     hidden_global_offset_x
      - .offset:         280
        .size:           8
        .value_kind:     hidden_global_offset_y
      - .offset:         288
        .size:           8
        .value_kind:     hidden_global_offset_z
      - .offset:         296
        .size:           2
        .value_kind:     hidden_grid_dims
      - .offset:         320
        .size:           8
        .value_kind:     hidden_multigrid_sync_arg
      - .offset:         352
        .size:           4
        .value_kind:     hidden_dynamic_lds_size
    .group_segment_fixed_size: 0
    .kernarg_segment_align: 8
    .kernarg_segment_size: 488
    .language:       OpenCL C
    .language_version:
      - 2
      - 0
    .max_flat_workgroup_size: 512
    .name:           _Z8fwd_mega4Args
    .private_segment_fixed_size: 0
    .sgpr_count:     108
    .sgpr_spill_count: 40
    .symbol:         _Z8fwd_mega4Args.kd
    .uniform_work_group_size: 1
    .uses_dynamic_stack: false
    .vgpr_count:     256
    .vgpr_spill_count: 0
    .wavefront_size: 64
